# v12
# baseline (speedup 1.0000x reference)
.LBB0_268:
	s_add_u32 s5, s26, 0x100
	s_addc_u32 s17, s27, 0
	s_add_u32 s24, s24, 0x80080
	v_mov_b32_e32 v0, 0
	s_addc_u32 s25, s25, 0
	s_mov_b32 s69, -2
	v_mov_b32_e32 v1, 0
	v_mov_b64_e32 v[2:3], 0
	v_mov_b64_e32 v[4:5], 0
	v_mov_b64_e32 v[6:7], 0
	v_mov_b64_e32 v[8:9], 0
	v_mov_b64_e32 v[10:11], 0
	v_mov_b64_e32 v[12:13], 0
	v_mov_b64_e32 v[14:15], 0
	v_mov_b64_e32 v[16:17], 0
	v_mov_b64_e32 v[18:19], 0
	v_mov_b64_e32 v[20:21], 0
	v_mov_b64_e32 v[22:23], 0
	v_mov_b64_e32 v[24:25], 0
	v_mov_b64_e32 v[26:27], 0
	v_mov_b64_e32 v[28:29], 0
	v_mov_b64_e32 v[30:31], 0
	v_mov_b64_e32 v[32:33], 0
	v_mov_b64_e32 v[34:35], 0
	v_mov_b64_e32 v[36:37], 0
	v_mov_b64_e32 v[38:39], 0
	v_mov_b64_e32 v[40:41], 0
	v_mov_b64_e32 v[42:43], 0
	v_mov_b64_e32 v[44:45], 0
	v_mov_b64_e32 v[46:47], 0
	v_mov_b64_e32 v[48:49], 0
	v_mov_b64_e32 v[50:51], 0
	v_mov_b64_e32 v[52:53], 0
	v_mov_b64_e32 v[54:55], 0
	v_mov_b64_e32 v[56:57], 0
	v_mov_b64_e32 v[58:59], 0
	v_mov_b64_e32 v[60:61], 0
	v_mov_b64_e32 v[62:63], 0
	v_mov_b64_e32 v[64:65], 0
	v_mov_b64_e32 v[66:67], 0
	v_mov_b64_e32 v[68:69], 0
	v_mov_b64_e32 v[70:71], 0
	v_mov_b64_e32 v[72:73], 0
	v_mov_b64_e32 v[74:75], 0
	v_mov_b64_e32 v[76:77], 0
	v_mov_b64_e32 v[78:79], 0
	v_mov_b64_e32 v[80:81], 0
	v_mov_b64_e32 v[82:83], 0
	v_mov_b64_e32 v[84:85], 0
	v_mov_b64_e32 v[86:87], 0
	v_mov_b64_e32 v[88:89], 0
	v_mov_b64_e32 v[90:91], 0
	v_mov_b64_e32 v[92:93], 0
	v_mov_b64_e32 v[94:95], 0
	v_mov_b64_e32 v[96:97], 0
	v_mov_b64_e32 v[98:99], 0
	v_mov_b64_e32 v[100:101], 0
	v_mov_b64_e32 v[102:103], 0
	v_mov_b64_e32 v[104:105], 0
	v_mov_b64_e32 v[106:107], 0
	v_mov_b64_e32 v[108:109], 0
	v_mov_b64_e32 v[110:111], 0
	v_mov_b64_e32 v[112:113], 0
	v_mov_b64_e32 v[114:115], 0
	v_mov_b64_e32 v[116:117], 0
	v_mov_b64_e32 v[118:119], 0
	v_mov_b64_e32 v[120:121], 0
	v_mov_b64_e32 v[122:123], 0
	v_mov_b64_e32 v[124:125], 0
	v_mov_b64_e32 v[126:127], 0

.LBB0_934:
	v_lshl_add_u64 v[8:9], s[8:9], 0, v[178:179]
	v_mov_b32_e32 v129, v179
	v_and_b32_e32 v7, 15, v3
	v_lshrrev_b32_e32 v16, 1, v3
	v_lshl_add_u64 v[10:11], s[8:9], 0, v[128:129]
	v_mov_b32_e32 v133, v179
	v_or_b32_e32 v138, s20, v7
	v_and_b32_e32 v139, 24, v16
	s_add_i32 m0, s22, 0x18000
	v_lshl_add_u64 v[8:9], v[8:9], 0, s[54:55]
	v_lshl_add_u64 v[12:13], s[6:7], 0, v[132:133]
	v_mov_b32_e32 v131, v179
	v_lshlrev_b32_e32 v16, 6, v138
	v_lshlrev_b32_e32 v17, 1, v139
	s_movk_i32 s10, 0x3c0
	s_waitcnt vmcnt(4)
	s_barrier
	global_load_lds_dwordx4 v[8:9], off
	v_lshl_add_u64 v[8:9], v[10:11], 0, s[54:55]
	s_add_i32 m0, s22, 0x1a000
	s_add_i32 s26, s22, 0x8000
	s_add_i32 s27, s22, 0xa000
	v_lshl_add_u64 v[14:15], s[6:7], 0, v[130:131]
	v_and_or_b32 v16, v16, s10, v17
	global_load_lds_dwordx4 v[8:9], off
	v_lshl_add_u64 v[8:9], v[12:13], 0, s[54:55]
	s_mov_b32 m0, s26
	s_add_u32 s10, s8, 0x100080
	global_load_lds_dwordx4 v[8:9], off
	v_lshl_add_u64 v[8:9], v[14:15], 0, s[54:55]
	s_mov_b32 m0, s27
	s_addc_u32 s11, s9, 0
	global_load_lds_dwordx4 v[8:9], off
	s_add_i32 m0, s22, 0x1c000
	global_load_lds_dwordx4 v178, s[10:11]
	s_add_i32 m0, s22, 0x1e000
	v_lshlrev_b32_e32 v3, 2, v3
	global_load_lds_dwordx4 v128, s[10:11]
	v_lshl_or_b32 v7, v7, 6, v17
	v_and_b32_e32 v3, 32, v3
	v_bitop3_b32 v140, v7, s19, v3 bitop3:0xde
	v_lshlrev_b32_e32 v3, 16, v0
	v_and_b32_e32 v3, 0xfffe0000, v3
	v_readlane_b32 s10, v253, 49
	v_lshl_add_u32 v1, v1, 13, v3
	v_and_b32_e32 v0, 1, v0
	s_add_u32 s10, s88, s10
	v_lshl_or_b32 v0, v0, 6, v1
	s_addc_u32 s11, s89, 0
	v_lshl_add_u32 v0, v2, 1, v0
	v_mov_b32_e32 v1, v179
	v_lshl_add_u64 v[134:135], s[10:11], 0, v[0:1]
	v_lshlrev_b32_e32 v0, 16, v4
	v_and_b32_e32 v0, 0xfffe0000, v0
	v_lshl_add_u32 v0, v5, 13, v0
	v_and_b32_e32 v1, 1, v4
	v_lshlrev_b32_e32 v18, 2, v138
	v_lshl_or_b32 v0, v1, 6, v0
	v_and_b32_e32 v18, 32, v18
	s_waitcnt vmcnt(6)
	v_lshl_add_u32 v0, v6, 1, v0
	v_mov_b32_e32 v1, v179
	v_bitop3_b32 v16, v16, s18, v18 bitop3:0xde
	v_lshl_add_u64 v[136:137], s[10:11], 0, v[0:1]
	v_mov_b32_e32 v0, 0
	s_mov_b32 s28, -2
	s_mov_b64 s[10:11], 0xb400080
	v_add_u32_e32 v141, 0, v16
	v_mov_b32_e32 v1, 0
	v_mov_b64_e32 v[2:3], 0
	v_mov_b64_e32 v[4:5], 0
	v_mov_b64_e32 v[6:7], 0
	v_mov_b64_e32 v[8:9], 0
	v_mov_b64_e32 v[10:11], 0
	v_mov_b64_e32 v[12:13], 0
	v_mov_b64_e32 v[14:15], 0
	v_mov_b64_e32 v[16:17], 0
	v_mov_b64_e32 v[18:19], 0
	v_mov_b64_e32 v[20:21], 0
	v_mov_b64_e32 v[22:23], 0
	v_mov_b64_e32 v[24:25], 0
	v_mov_b64_e32 v[26:27], 0
	v_mov_b64_e32 v[28:29], 0
	v_mov_b64_e32 v[30:31], 0
	v_mov_b64_e32 v[32:33], 0
	v_mov_b64_e32 v[34:35], 0
	v_mov_b64_e32 v[36:37], 0
	v_mov_b64_e32 v[38:39], 0
	v_mov_b64_e32 v[40:41], 0
	v_mov_b64_e32 v[42:43], 0
	v_mov_b64_e32 v[44:45], 0
	v_mov_b64_e32 v[46:47], 0
	v_mov_b64_e32 v[48:49], 0
	v_mov_b64_e32 v[50:51], 0
	v_mov_b64_e32 v[52:53], 0
	v_mov_b64_e32 v[54:55], 0
	v_mov_b64_e32 v[56:57], 0
	v_mov_b64_e32 v[58:59], 0
	v_mov_b64_e32 v[60:61], 0
	v_mov_b64_e32 v[62:63], 0
	v_mov_b64_e32 v[64:65], 0
	v_mov_b64_e32 v[66:67], 0
	v_mov_b64_e32 v[68:69], 0
	v_mov_b64_e32 v[70:71], 0
	v_mov_b64_e32 v[72:73], 0
	v_mov_b64_e32 v[74:75], 0
	v_mov_b64_e32 v[76:77], 0
	v_mov_b64_e32 v[78:79], 0
	v_mov_b64_e32 v[80:81], 0
	v_mov_b64_e32 v[82:83], 0
	v_mov_b64_e32 v[84:85], 0
	v_mov_b64_e32 v[86:87], 0
	v_mov_b64_e32 v[88:89], 0
	v_mov_b64_e32 v[90:91], 0
	v_mov_b64_e32 v[92:93], 0
	v_mov_b64_e32 v[94:95], 0
	v_mov_b64_e32 v[96:97], 0
	v_mov_b64_e32 v[98:99], 0
	v_mov_b64_e32 v[100:101], 0
	v_mov_b64_e32 v[102:103], 0
	v_mov_b64_e32 v[104:105], 0
	v_mov_b64_e32 v[106:107], 0
	v_mov_b64_e32 v[108:109], 0
	v_mov_b64_e32 v[110:111], 0
	v_mov_b64_e32 v[112:113], 0
	v_mov_b64_e32 v[114:115], 0
	v_mov_b64_e32 v[116:117], 0
	v_mov_b64_e32 v[118:119], 0
	v_mov_b64_e32 v[120:121], 0
	v_mov_b64_e32 v[122:123], 0
	v_mov_b64_e32 v[124:125], 0
	v_mov_b64_e32 v[126:127], 0
	s_barrier

.LBB0_942:
	v_lshl_add_u64 v[8:9], s[8:9], 0, v[178:179]
	v_and_b32_e32 v7, 15, v3
	v_lshrrev_b32_e32 v12, 1, v3
	v_or_b32_e32 v138, s20, v7
	v_and_b32_e32 v139, 24, v12
	s_add_i32 m0, s22, 0x18000
	v_lshl_add_u64 v[8:9], v[8:9], 0, s[54:55]
	v_mov_b32_e32 v129, v179
	v_lshlrev_b32_e32 v12, 6, v138
	v_lshlrev_b32_e32 v13, 1, v139
	s_movk_i32 s10, 0x3c0
	v_lshlrev_b32_e32 v14, 2, v138
	s_waitcnt vmcnt(4)
	s_barrier
	global_load_lds_dwordx4 v[8:9], off
	s_add_i32 m0, s22, 0x1a000
	v_lshl_add_u64 v[10:11], s[8:9], 0, v[128:129]
	v_and_or_b32 v12, v12, s10, v13
	v_and_b32_e32 v14, 32, v14
	v_lshlrev_b32_e32 v3, 2, v3
	s_add_u32 s10, s88, 0xc300080
	v_mov_b32_e32 v133, v179
	v_bitop3_b32 v12, v12, s18, v14 bitop3:0xde
	v_lshl_or_b32 v7, v7, 6, v13
	v_and_b32_e32 v3, 32, v3
	v_lshl_add_u64 v[8:9], v[10:11], 0, s[54:55]
	s_addc_u32 s11, s89, 0
	s_add_i32 s18, s22, 0x8000
	v_mov_b32_e32 v131, v179
	v_bitop3_b32 v140, v7, s19, v3 bitop3:0xde
	global_load_lds_dwordx4 v[8:9], off
	s_mov_b32 m0, s18
	s_add_i32 s19, s22, 0xa000
	global_load_lds_dwordx4 v132, s[10:11]
	v_lshl_add_u64 v[8:9], s[10:11], 0, v[130:131]
	s_add_u32 s10, s8, 0x20080
	s_mov_b32 m0, s19
	s_addc_u32 s11, s9, 0
	global_load_lds_dwordx4 v[8:9], off
	s_add_i32 m0, s22, 0x1c000
	global_load_lds_dwordx4 v178, s[10:11]
	s_add_i32 m0, s22, 0x1e000
	v_lshlrev_b32_e32 v3, 13, v0
	global_load_lds_dwordx4 v128, s[10:11]
	v_and_b32_e32 v3, 0xffffc000, v3
	v_lshl_add_u32 v1, v1, 10, v3
	v_and_b32_e32 v0, 1, v0
	v_lshl_or_b32 v0, v0, 6, v1
	v_lshl_add_u32 v0, v2, 1, v0
	v_mov_b32_e32 v1, v179
	v_lshl_add_u64 v[134:135], s[88:89], 0, v[0:1]
	v_lshlrev_b32_e32 v0, 13, v4
	v_and_b32_e32 v0, 0xffffc000, v0
	v_lshl_add_u32 v0, v5, 10, v0
	v_and_b32_e32 v1, 1, v4
	v_lshl_or_b32 v0, v1, 6, v0
	s_waitcnt vmcnt(6)
	v_lshl_add_u32 v0, v6, 1, v0
	v_mov_b32_e32 v1, v179
	v_lshl_add_u64 v[136:137], s[88:89], 0, v[0:1]
	v_mov_b32_e32 v0, 0
	s_mov_b32 s20, -2
	s_mov_b64 s[10:11], 0xc320080
	v_add_u32_e32 v141, 0, v12
	v_mov_b32_e32 v1, 0
	v_mov_b64_e32 v[2:3], 0
	v_mov_b64_e32 v[4:5], 0
	v_mov_b64_e32 v[6:7], 0
	v_mov_b64_e32 v[8:9], 0
	v_mov_b64_e32 v[10:11], 0
	v_mov_b64_e32 v[12:13], 0
	v_mov_b64_e32 v[14:15], 0
	v_mov_b64_e32 v[16:17], 0
	v_mov_b64_e32 v[18:19], 0
	v_mov_b64_e32 v[20:21], 0
	v_mov_b64_e32 v[22:23], 0
	v_mov_b64_e32 v[24:25], 0
	v_mov_b64_e32 v[26:27], 0
	v_mov_b64_e32 v[28:29], 0
	v_mov_b64_e32 v[30:31], 0
	v_mov_b64_e32 v[32:33], 0
	v_mov_b64_e32 v[34:35], 0
	v_mov_b64_e32 v[36:37], 0
	v_mov_b64_e32 v[38:39], 0
	v_mov_b64_e32 v[40:41], 0
	v_mov_b64_e32 v[42:43], 0
	v_mov_b64_e32 v[44:45], 0
	v_mov_b64_e32 v[46:47], 0
	v_mov_b64_e32 v[48:49], 0
	v_mov_b64_e32 v[50:51], 0
	v_mov_b64_e32 v[52:53], 0
	v_mov_b64_e32 v[54:55], 0
	v_mov_b64_e32 v[56:57], 0
	v_mov_b64_e32 v[58:59], 0
	v_mov_b64_e32 v[60:61], 0
	v_mov_b64_e32 v[62:63], 0
	v_mov_b64_e32 v[64:65], 0
	v_mov_b64_e32 v[66:67], 0
	v_mov_b64_e32 v[68:69], 0
	v_mov_b64_e32 v[70:71], 0
	v_mov_b64_e32 v[72:73], 0
	v_mov_b64_e32 v[74:75], 0
	v_mov_b64_e32 v[76:77], 0
	v_mov_b64_e32 v[78:79], 0
	v_mov_b64_e32 v[80:81], 0
	v_mov_b64_e32 v[82:83], 0
	v_mov_b64_e32 v[84:85], 0
	v_mov_b64_e32 v[86:87], 0
	v_mov_b64_e32 v[88:89], 0
	v_mov_b64_e32 v[90:91], 0
	v_mov_b64_e32 v[92:93], 0
	v_mov_b64_e32 v[94:95], 0
	v_mov_b64_e32 v[96:97], 0
	v_mov_b64_e32 v[98:99], 0
	v_mov_b64_e32 v[100:101], 0
	v_mov_b64_e32 v[102:103], 0
	v_mov_b64_e32 v[104:105], 0
	v_mov_b64_e32 v[106:107], 0
	v_mov_b64_e32 v[108:109], 0
	v_mov_b64_e32 v[110:111], 0
	v_mov_b64_e32 v[112:113], 0
	v_mov_b64_e32 v[114:115], 0
	v_mov_b64_e32 v[116:117], 0
	v_mov_b64_e32 v[118:119], 0
	v_mov_b64_e32 v[120:121], 0
	v_mov_b64_e32 v[122:123], 0
	v_mov_b64_e32 v[124:125], 0
	v_mov_b64_e32 v[126:127], 0
	s_barrier

.LBB0_1076:
	s_add_u32 s5, s18, 0x100
	v_mov_b32_e32 v0, 0
	s_addc_u32 s62, s19, 0
	s_mov_b32 s63, -2
	v_mov_b32_e32 v1, 0
	v_mov_b64_e32 v[2:3], 0
	v_mov_b64_e32 v[4:5], 0
	v_mov_b64_e32 v[6:7], 0
	v_mov_b64_e32 v[8:9], 0
	v_mov_b64_e32 v[10:11], 0
	v_mov_b64_e32 v[12:13], 0
	v_mov_b64_e32 v[14:15], 0
	v_mov_b64_e32 v[16:17], 0
	v_mov_b64_e32 v[18:19], 0
	v_mov_b64_e32 v[20:21], 0
	v_mov_b64_e32 v[22:23], 0
	v_mov_b64_e32 v[24:25], 0
	v_mov_b64_e32 v[26:27], 0
	v_mov_b64_e32 v[28:29], 0
	v_mov_b64_e32 v[30:31], 0
	v_mov_b64_e32 v[32:33], 0
	v_mov_b64_e32 v[34:35], 0
	v_mov_b64_e32 v[36:37], 0
	v_mov_b64_e32 v[38:39], 0
	v_mov_b64_e32 v[40:41], 0
	v_mov_b64_e32 v[42:43], 0
	v_mov_b64_e32 v[44:45], 0
	v_mov_b64_e32 v[46:47], 0
	v_mov_b64_e32 v[48:49], 0
	v_mov_b64_e32 v[50:51], 0
	v_mov_b64_e32 v[52:53], 0
	v_mov_b64_e32 v[54:55], 0
	v_mov_b64_e32 v[56:57], 0
	v_mov_b64_e32 v[58:59], 0
	v_mov_b64_e32 v[60:61], 0
	v_mov_b64_e32 v[62:63], 0
	v_mov_b64_e32 v[64:65], 0
	v_mov_b64_e32 v[66:67], 0
	v_mov_b64_e32 v[68:69], 0
	v_mov_b64_e32 v[70:71], 0
	v_mov_b64_e32 v[72:73], 0
	v_mov_b64_e32 v[74:75], 0
	v_mov_b64_e32 v[76:77], 0
	v_mov_b64_e32 v[78:79], 0
	v_mov_b64_e32 v[80:81], 0
	v_mov_b64_e32 v[82:83], 0
	v_mov_b64_e32 v[84:85], 0
	v_mov_b64_e32 v[86:87], 0
	v_mov_b64_e32 v[88:89], 0
	v_mov_b64_e32 v[90:91], 0
	v_mov_b64_e32 v[92:93], 0
	v_mov_b64_e32 v[94:95], 0
	v_mov_b64_e32 v[96:97], 0
	v_mov_b64_e32 v[98:99], 0
	v_mov_b64_e32 v[100:101], 0
	v_mov_b64_e32 v[102:103], 0
	v_mov_b64_e32 v[104:105], 0
	v_mov_b64_e32 v[106:107], 0
	v_mov_b64_e32 v[108:109], 0
	v_mov_b64_e32 v[110:111], 0
	v_mov_b64_e32 v[112:113], 0
	v_mov_b64_e32 v[114:115], 0
	v_mov_b64_e32 v[116:117], 0
	v_mov_b64_e32 v[118:119], 0
	v_mov_b64_e32 v[120:121], 0
	v_mov_b64_e32 v[122:123], 0
	v_mov_b64_e32 v[124:125], 0
	v_mov_b64_e32 v[126:127], 0

.LBB0_1197:
	s_add_u32 s35, s66, 0x100
	s_addc_u32 s75, s67, 0
	s_add_u32 s8, s8, 0x80080
	v_mov_b32_e32 v0, 0
	s_addc_u32 s9, s9, 0
	s_mov_b32 s76, -2
	v_mov_b32_e32 v1, 0
	v_mov_b64_e32 v[2:3], 0
	v_mov_b64_e32 v[4:5], 0
	v_mov_b64_e32 v[6:7], 0
	v_mov_b64_e32 v[8:9], 0
	v_mov_b64_e32 v[10:11], 0
	v_mov_b64_e32 v[12:13], 0
	v_mov_b64_e32 v[14:15], 0
	v_mov_b64_e32 v[16:17], 0
	v_mov_b64_e32 v[18:19], 0
	v_mov_b64_e32 v[20:21], 0
	v_mov_b64_e32 v[22:23], 0
	v_mov_b64_e32 v[24:25], 0
	v_mov_b64_e32 v[26:27], 0
	v_mov_b64_e32 v[28:29], 0
	v_mov_b64_e32 v[30:31], 0
	v_mov_b64_e32 v[32:33], 0
	v_mov_b64_e32 v[34:35], 0
	v_mov_b64_e32 v[36:37], 0
	v_mov_b64_e32 v[38:39], 0
	v_mov_b64_e32 v[40:41], 0
	v_mov_b64_e32 v[42:43], 0
	v_mov_b64_e32 v[44:45], 0
	v_mov_b64_e32 v[46:47], 0
	v_mov_b64_e32 v[48:49], 0
	v_mov_b64_e32 v[50:51], 0
	v_mov_b64_e32 v[52:53], 0
	v_mov_b64_e32 v[54:55], 0
	v_mov_b64_e32 v[56:57], 0
	v_mov_b64_e32 v[58:59], 0
	v_mov_b64_e32 v[60:61], 0
	v_mov_b64_e32 v[62:63], 0
	v_mov_b64_e32 v[64:65], 0
	v_mov_b64_e32 v[66:67], 0
	v_mov_b64_e32 v[68:69], 0
	v_mov_b64_e32 v[70:71], 0
	v_mov_b64_e32 v[72:73], 0
	v_mov_b64_e32 v[74:75], 0
	v_mov_b64_e32 v[76:77], 0
	v_mov_b64_e32 v[78:79], 0
	v_mov_b64_e32 v[80:81], 0
	v_mov_b64_e32 v[82:83], 0
	v_mov_b64_e32 v[84:85], 0
	v_mov_b64_e32 v[86:87], 0
	v_mov_b64_e32 v[88:89], 0
	v_mov_b64_e32 v[90:91], 0
	v_mov_b64_e32 v[92:93], 0
	v_mov_b64_e32 v[94:95], 0
	v_mov_b64_e32 v[96:97], 0
	v_mov_b64_e32 v[98:99], 0
	v_mov_b64_e32 v[100:101], 0
	v_mov_b64_e32 v[102:103], 0
	v_mov_b64_e32 v[104:105], 0
	v_mov_b64_e32 v[106:107], 0
	v_mov_b64_e32 v[108:109], 0
	v_mov_b64_e32 v[110:111], 0
	v_mov_b64_e32 v[112:113], 0
	v_mov_b64_e32 v[114:115], 0
	v_mov_b64_e32 v[116:117], 0
	v_mov_b64_e32 v[118:119], 0
	v_mov_b64_e32 v[120:121], 0
	v_mov_b64_e32 v[122:123], 0
	v_mov_b64_e32 v[124:125], 0
	v_mov_b64_e32 v[126:127], 0

.LBB0_1233:
	s_or_b64 exec, exec, s[78:79]
	s_waitcnt lgkmcnt(0)
	v_cndmask_b32_e64 v110, v88, v110, s[4:5]
	v_cndmask_b32_e64 v96, v92, v122, s[4:5]
	v_cndmask_b32_e64 v122, v80, v88, s[6:7]
	v_mul_f32_dpp v110, v110, v154 row_ror:1 row_mask:0xf bank_mask:0xf bound_ctrl:1
	v_fmac_f32_e32 v110, v146, v88
	v_fmac_f32_dpp v110, v122, v150 row_ror:15 row_mask:0xf bank_mask:0xf bound_ctrl:1
	v_cndmask_b32_e64 v111, v89, v111, s[4:5]
	v_add_f32_e32 v110, v158, v110
	v_mul_f32_e32 v122, 0xbfb8aa3b, v110
	v_cndmask_b32_e64 v97, v93, v123, s[4:5]
	v_cndmask_b32_e64 v123, v81, v89, s[6:7]
	v_exp_f32_e32 v122, v122
	v_mul_f32_dpp v111, v111, v155 row_ror:1 row_mask:0xf bank_mask:0xf bound_ctrl:1
	v_fmac_f32_e32 v111, v147, v89
	v_fmac_f32_dpp v111, v123, v151 row_ror:15 row_mask:0xf bank_mask:0xf bound_ctrl:1
	v_add_f32_e32 v111, v159, v111
	v_add_f32_e32 v122, 1.0, v122
	v_mul_f32_e32 v123, 0xbfb8aa3b, v111
	v_rcp_f32_e32 v122, v122
	v_exp_f32_e32 v123, v123
	v_cndmask_b32_e64 v114, v84, v92, s[6:7]
	v_mul_f32_e32 v110, v110, v122
	v_add_f32_e32 v122, 1.0, v123
	v_mul_f32_dpp v96, v96, v130 row_ror:1 row_mask:0xf bank_mask:0xf bound_ctrl:1
	v_rcp_f32_e32 v122, v122
	v_fmac_f32_e32 v96, v92, v138
	v_cndmask_b32_e64 v112, v90, v112, s[4:5]
	v_fmac_f32_dpp v96, v114, v134 row_ror:15 row_mask:0xf bank_mask:0xf bound_ctrl:1
	v_add_f32_e32 v96, v142, v96
	v_cndmask_b32_e64 v102, v94, v124, s[4:5]
	v_cndmask_b32_e64 v124, v82, v90, s[6:7]
	v_mul_f32_e32 v96, v96, v110
	v_mul_f32_e32 v110, v111, v122
	v_mul_f32_dpp v111, v112, v156 row_ror:1 row_mask:0xf bank_mask:0xf bound_ctrl:1
	v_fmac_f32_e32 v111, v148, v90
	v_fmac_f32_dpp v111, v124, v152 row_ror:15 row_mask:0xf bank_mask:0xf bound_ctrl:1
	v_add_f32_e32 v111, v160, v111
	v_mul_f32_e32 v112, 0xbfb8aa3b, v111
	v_cndmask_b32_e64 v115, v85, v93, s[6:7]
	v_mul_f32_dpp v97, v97, v131 row_ror:1 row_mask:0xf bank_mask:0xf bound_ctrl:1
	v_exp_f32_e32 v112, v112
	v_fmac_f32_e32 v97, v93, v139
	v_cndmask_b32_e64 v113, v91, v113, s[4:5]
	v_fmac_f32_dpp v97, v115, v135 row_ror:15 row_mask:0xf bank_mask:0xf bound_ctrl:1
	v_add_f32_e32 v97, v143, v97
	v_cndmask_b32_e64 v103, v95, v125, s[4:5]
	v_cndmask_b32_e64 v125, v83, v91, s[6:7]
	v_mul_f32_e32 v97, v97, v110
	v_add_f32_e32 v110, 1.0, v112
	v_mul_f32_dpp v112, v113, v157 row_ror:1 row_mask:0xf bank_mask:0xf bound_ctrl:1
	v_fmac_f32_e32 v112, v149, v91
	v_fmac_f32_dpp v112, v125, v153 row_ror:15 row_mask:0xf bank_mask:0xf bound_ctrl:1
	v_add_f32_e32 v112, v161, v112
	v_mul_f32_e32 v113, 0xbfb8aa3b, v112
	v_rcp_f32_e32 v110, v110
	v_exp_f32_e32 v113, v113
	v_mul_f32_e32 v110, v111, v110
	v_add_f32_e32 v111, 1.0, v113
	v_cndmask_b32_e64 v118, v86, v94, s[6:7]
	v_mul_f32_dpp v102, v102, v132 row_ror:1 row_mask:0xf bank_mask:0xf bound_ctrl:1
	v_rcp_f32_e32 v111, v111
	v_cndmask_b32_e64 v119, v87, v95, s[6:7]
	v_fmac_f32_e32 v102, v94, v140
	v_mul_f32_dpp v103, v103, v133 row_ror:1 row_mask:0xf bank_mask:0xf bound_ctrl:1
	v_fmac_f32_dpp v102, v118, v136 row_ror:15 row_mask:0xf bank_mask:0xf bound_ctrl:1
	v_fmac_f32_e32 v103, v95, v141
	v_add_f32_e32 v102, v144, v102
	v_fmac_f32_dpp v103, v119, v137 row_ror:15 row_mask:0xf bank_mask:0xf bound_ctrl:1
	v_mul_f32_e32 v102, v102, v110
	v_mul_f32_e32 v110, v112, v111
	v_add_f32_e32 v103, v145, v103
	v_mul_f32_e32 v103, v103, v110
	v_cvt_pk_bf16_f32 v96, v96, v97
	v_cvt_pk_bf16_f32 v97, v102, v103
	s_mov_b64 s[100:101], 0xa000
	v_lshl_add_u64 v[240:241], v[198:199], 0, s[100:101]
	global_load_dwordx4 v[164:167], v[198:199], off offset:16
	global_load_dwordx4 v[168:171], v[240:241], off offset:3088
	s_mov_b64 s[100:101], 0x15000
	v_lshl_add_u64 v[240:241], v[198:199], 0, s[100:101]
	global_load_dwordx4 v[172:175], v[240:241], off offset:2064
	global_load_dwordx4 v[204:207], v[196:197], off offset:16
	s_mov_b64 s[100:101], 0x5000
	v_lshl_add_u64 v[240:241], v[198:199], 0, s[100:101]
	global_load_dwordx4 v[212:215], v[240:241], off offset:1552
	s_mov_b64 s[100:101], 0x10000
	v_lshl_add_u64 v[240:241], v[198:199], 0, s[100:101]
	global_load_dwordx4 v[228:231], v[240:241], off offset:528
	s_mov_b64 s[100:101], 0x1a000
	v_lshl_add_u64 v[240:241], v[198:199], 0, s[100:101]
	global_load_dwordx4 v[232:235], v[240:241], off offset:3600
	s_mov_b64 s[100:101], 0x5000
	v_lshl_add_u64 v[240:241], v[196:197], 0, s[100:101]
	global_load_dwordx4 v[236:239], v[240:241], off offset:1552
	v_cndmask_b32_e64 v88, v80, v88, s[4:5]
	v_cndmask_b32_e64 v112, v72, v80, s[6:7]
	v_cndmask_b32_e64 v89, v81, v89, s[4:5]
	v_mul_f32_dpp v88, v88, v154 row_ror:1 row_mask:0xf bank_mask:0xf bound_ctrl:1
	v_fmac_f32_e32 v88, v80, v146
	v_fmac_f32_dpp v88, v112, v150 row_ror:15 row_mask:0xf bank_mask:0xf bound_ctrl:1
	v_add_f32_e32 v88, v158, v88
	v_mul_f32_e32 v112, 0xbfb8aa3b, v88
	v_cndmask_b32_e64 v113, v73, v81, s[6:7]
	v_exp_f32_e32 v112, v112
	v_mul_f32_dpp v89, v89, v155 row_ror:1 row_mask:0xf bank_mask:0xf bound_ctrl:1
	v_fmac_f32_e32 v89, v81, v147
	v_fmac_f32_dpp v89, v113, v151 row_ror:15 row_mask:0xf bank_mask:0xf bound_ctrl:1
	v_add_f32_e32 v89, v159, v89
	v_cndmask_b32_e64 v92, v84, v92, s[4:5]
	v_cndmask_b32_e64 v90, v82, v90, s[4:5]
	v_add_f32_e32 v112, 1.0, v112
	v_mul_f32_e32 v113, 0xbfb8aa3b, v89
	v_rcp_f32_e32 v112, v112
	v_exp_f32_e32 v113, v113
	v_cndmask_b32_e64 v102, v76, v84, s[6:7]
	v_cndmask_b32_e64 v114, v74, v82, s[6:7]
	v_mul_f32_dpp v92, v92, v130 row_ror:1 row_mask:0xf bank_mask:0xf bound_ctrl:1
	v_mul_f32_dpp v90, v90, v156 row_ror:1 row_mask:0xf bank_mask:0xf bound_ctrl:1
	v_fmac_f32_e32 v92, v84, v138
	v_fmac_f32_e32 v90, v82, v148
	v_cndmask_b32_e64 v93, v85, v93, s[4:5]
	v_fmac_f32_dpp v92, v102, v134 row_ror:15 row_mask:0xf bank_mask:0xf bound_ctrl:1
	v_fmac_f32_dpp v90, v114, v152 row_ror:15 row_mask:0xf bank_mask:0xf bound_ctrl:1
	v_mul_f32_e32 v88, v88, v112
	v_add_f32_e32 v112, 1.0, v113
	v_add_f32_e32 v92, v142, v92
	v_add_f32_e32 v90, v160, v90
	v_rcp_f32_e32 v112, v112
	v_mul_f32_e32 v88, v92, v88
	v_mul_f32_dpp v92, v93, v131 row_ror:1 row_mask:0xf bank_mask:0xf bound_ctrl:1
	v_mul_f32_e32 v93, 0xbfb8aa3b, v90
	v_cndmask_b32_e64 v91, v83, v91, s[4:5]
	v_cndmask_b32_e64 v103, v77, v85, s[6:7]
	v_exp_f32_e32 v93, v93
	v_fmac_f32_e32 v92, v85, v139
	v_cndmask_b32_e64 v115, v75, v83, s[6:7]
	v_fmac_f32_dpp v92, v103, v135 row_ror:15 row_mask:0xf bank_mask:0xf bound_ctrl:1
	v_mul_f32_dpp v91, v91, v157 row_ror:1 row_mask:0xf bank_mask:0xf bound_ctrl:1
	v_mul_f32_e32 v89, v89, v112
	v_add_f32_e32 v92, v143, v92
	v_fmac_f32_e32 v91, v83, v149
	v_mul_f32_e32 v89, v92, v89
	v_add_f32_e32 v92, 1.0, v93
	v_fmac_f32_dpp v91, v115, v153 row_ror:15 row_mask:0xf bank_mask:0xf bound_ctrl:1
	v_rcp_f32_e32 v92, v92
	v_add_f32_e32 v91, v161, v91
	v_mul_f32_e32 v93, 0xbfb8aa3b, v91
	v_cndmask_b32_e64 v94, v86, v94, s[4:5]
	v_exp_f32_e32 v93, v93
	v_cndmask_b32_e64 v110, v78, v86, s[6:7]
	v_mul_f32_e32 v90, v90, v92
	v_mul_f32_dpp v92, v94, v132 row_ror:1 row_mask:0xf bank_mask:0xf bound_ctrl:1
	v_fmac_f32_e32 v92, v86, v140
	v_cndmask_b32_e64 v95, v87, v95, s[4:5]
	v_add_f32_e32 v93, 1.0, v93
	v_fmac_f32_dpp v92, v110, v136 row_ror:15 row_mask:0xf bank_mask:0xf bound_ctrl:1
	v_rcp_f32_e32 v93, v93
	v_add_f32_e32 v92, v144, v92
	v_cndmask_b32_e64 v111, v79, v87, s[6:7]
	v_mul_f32_e32 v90, v92, v90
	v_mul_f32_dpp v92, v95, v133 row_ror:1 row_mask:0xf bank_mask:0xf bound_ctrl:1
	v_fmac_f32_e32 v92, v87, v141
	v_fmac_f32_dpp v92, v111, v137 row_ror:15 row_mask:0xf bank_mask:0xf bound_ctrl:1
	v_mul_f32_e32 v91, v91, v93
	v_add_f32_e32 v92, v145, v92
	v_mul_f32_e32 v91, v92, v91
	v_cvt_pk_bf16_f32 v88, v88, v89
	v_cvt_pk_bf16_f32 v89, v90, v91
	v_cndmask_b32_e64 v80, v72, v80, s[4:5]
	v_cndmask_b32_e64 v94, v64, v72, s[6:7]
	v_cndmask_b32_e64 v81, v73, v81, s[4:5]
	v_mul_f32_dpp v80, v80, v154 row_ror:1 row_mask:0xf bank_mask:0xf bound_ctrl:1
	v_fmac_f32_e32 v80, v72, v146
	v_fmac_f32_dpp v80, v94, v150 row_ror:15 row_mask:0xf bank_mask:0xf bound_ctrl:1
	v_add_f32_e32 v80, v158, v80
	v_mul_f32_e32 v94, 0xbfb8aa3b, v80
	v_cndmask_b32_e64 v95, v65, v73, s[6:7]
	v_exp_f32_e32 v94, v94
	v_mul_f32_dpp v81, v81, v155 row_ror:1 row_mask:0xf bank_mask:0xf bound_ctrl:1
	v_fmac_f32_e32 v81, v73, v147
	v_fmac_f32_dpp v81, v95, v151 row_ror:15 row_mask:0xf bank_mask:0xf bound_ctrl:1
	v_add_f32_e32 v81, v159, v81
	v_cndmask_b32_e64 v84, v76, v84, s[4:5]
	v_cndmask_b32_e64 v82, v74, v82, s[4:5]
	v_add_f32_e32 v94, 1.0, v94
	v_mul_f32_e32 v95, 0xbfb8aa3b, v81
	v_rcp_f32_e32 v94, v94
	v_exp_f32_e32 v95, v95
	v_cndmask_b32_e64 v90, v68, v76, s[6:7]
	v_cndmask_b32_e64 v102, v66, v74, s[6:7]
	v_mul_f32_dpp v84, v84, v130 row_ror:1 row_mask:0xf bank_mask:0xf bound_ctrl:1
	v_mul_f32_dpp v82, v82, v156 row_ror:1 row_mask:0xf bank_mask:0xf bound_ctrl:1
	v_fmac_f32_e32 v84, v76, v138
	v_fmac_f32_e32 v82, v74, v148
	v_cndmask_b32_e64 v85, v77, v85, s[4:5]
	v_fmac_f32_dpp v84, v90, v134 row_ror:15 row_mask:0xf bank_mask:0xf bound_ctrl:1
	v_fmac_f32_dpp v82, v102, v152 row_ror:15 row_mask:0xf bank_mask:0xf bound_ctrl:1
	v_mul_f32_e32 v80, v80, v94
	v_add_f32_e32 v94, 1.0, v95
	v_add_f32_e32 v84, v142, v84
	v_add_f32_e32 v82, v160, v82
	v_rcp_f32_e32 v94, v94
	v_mul_f32_e32 v80, v84, v80
	v_mul_f32_dpp v84, v85, v131 row_ror:1 row_mask:0xf bank_mask:0xf bound_ctrl:1
	v_mul_f32_e32 v85, 0xbfb8aa3b, v82
	v_cndmask_b32_e64 v83, v75, v83, s[4:5]
	v_cndmask_b32_e64 v91, v69, v77, s[6:7]
	v_exp_f32_e32 v85, v85
	v_fmac_f32_e32 v84, v77, v139
	v_cndmask_b32_e64 v103, v67, v75, s[6:7]
	v_fmac_f32_dpp v84, v91, v135 row_ror:15 row_mask:0xf bank_mask:0xf bound_ctrl:1
	v_mul_f32_dpp v83, v83, v157 row_ror:1 row_mask:0xf bank_mask:0xf bound_ctrl:1
	v_mul_f32_e32 v81, v81, v94
	v_add_f32_e32 v84, v143, v84
	v_fmac_f32_e32 v83, v75, v149
	v_mul_f32_e32 v81, v84, v81
	v_add_f32_e32 v84, 1.0, v85
	v_fmac_f32_dpp v83, v103, v153 row_ror:15 row_mask:0xf bank_mask:0xf bound_ctrl:1
	v_rcp_f32_e32 v84, v84
	v_add_f32_e32 v83, v161, v83
	v_mul_f32_e32 v85, 0xbfb8aa3b, v83
	v_cndmask_b32_e64 v86, v78, v86, s[4:5]
	v_exp_f32_e32 v85, v85
	v_cndmask_b32_e64 v92, v70, v78, s[6:7]
	v_mul_f32_e32 v82, v82, v84
	v_mul_f32_dpp v84, v86, v132 row_ror:1 row_mask:0xf bank_mask:0xf bound_ctrl:1
	v_fmac_f32_e32 v84, v78, v140
	v_cndmask_b32_e64 v87, v79, v87, s[4:5]
	v_add_f32_e32 v85, 1.0, v85
	v_fmac_f32_dpp v84, v92, v136 row_ror:15 row_mask:0xf bank_mask:0xf bound_ctrl:1
	v_rcp_f32_e32 v85, v85
	v_add_f32_e32 v84, v144, v84
	v_cndmask_b32_e64 v93, v71, v79, s[6:7]
	v_mul_f32_e32 v82, v84, v82
	v_mul_f32_dpp v84, v87, v133 row_ror:1 row_mask:0xf bank_mask:0xf bound_ctrl:1
	v_fmac_f32_e32 v84, v79, v141
	v_fmac_f32_dpp v84, v93, v137 row_ror:15 row_mask:0xf bank_mask:0xf bound_ctrl:1
	v_mul_f32_e32 v83, v83, v85
	v_add_f32_e32 v84, v145, v84
	v_mul_f32_e32 v83, v84, v83
	v_cvt_pk_bf16_f32 v80, v80, v81
	v_cvt_pk_bf16_f32 v81, v82, v83
	v_cndmask_b32_e64 v72, v64, v72, s[4:5]
	v_cndmask_b32_e64 v86, v98, v64, s[6:7]
	v_cndmask_b32_e64 v73, v65, v73, s[4:5]
	v_mul_f32_dpp v72, v72, v154 row_ror:1 row_mask:0xf bank_mask:0xf bound_ctrl:1
	v_mov_b32_dpp v86, v86 row_ror:15 row_mask:0xf bank_mask:0xf bound_ctrl:1
	v_fmac_f32_e32 v72, v146, v64
	v_fmac_f32_e32 v72, v150, v86
	v_add_f32_e32 v64, v158, v72
	v_mul_f32_e32 v72, 0xbfb8aa3b, v64
	v_exp_f32_e32 v72, v72
	v_cndmask_b32_e64 v87, v99, v65, s[6:7]
	v_mul_f32_dpp v73, v73, v155 row_ror:1 row_mask:0xf bank_mask:0xf bound_ctrl:1
	v_fmac_f32_e32 v73, v147, v65
	v_mov_b32_dpp v86, v87 row_ror:15 row_mask:0xf bank_mask:0xf bound_ctrl:1
	v_fmac_f32_e32 v73, v151, v86
	v_add_f32_e32 v72, 1.0, v72
	v_add_f32_e32 v65, v159, v73
	v_rcp_f32_e32 v72, v72
	v_mul_f32_e32 v73, 0xbfb8aa3b, v65
	v_exp_f32_e32 v73, v73
	v_cndmask_b32_e64 v76, v68, v76, s[4:5]
	v_mul_f32_e32 v64, v64, v72
	v_cndmask_b32_e64 v82, v106, v68, s[6:7]
	v_mul_f32_dpp v72, v76, v130 row_ror:1 row_mask:0xf bank_mask:0xf bound_ctrl:1
	v_fmac_f32_e32 v72, v68, v138
	v_add_f32_e32 v68, 1.0, v73
	v_rcp_f32_e32 v68, v68
	v_cndmask_b32_e64 v77, v69, v77, s[4:5]
	v_cndmask_b32_e64 v74, v66, v74, s[4:5]
	v_cndmask_b32_e64 v83, v107, v69, s[6:7]
	v_mul_f32_e32 v65, v65, v68
	v_mul_f32_dpp v68, v77, v131 row_ror:1 row_mask:0xf bank_mask:0xf bound_ctrl:1
	v_cndmask_b32_e64 v90, v100, v66, s[6:7]
	v_fmac_f32_e32 v68, v69, v139
	v_mul_f32_dpp v69, v74, v156 row_ror:1 row_mask:0xf bank_mask:0xf bound_ctrl:1
	v_mov_b32_dpp v87, v90 row_ror:15 row_mask:0xf bank_mask:0xf bound_ctrl:1
	v_fmac_f32_e32 v69, v148, v66
	v_fmac_f32_e32 v69, v152, v87
	v_add_f32_e32 v66, v160, v69
	v_mul_f32_e32 v69, 0xbfb8aa3b, v66
	v_exp_f32_e32 v69, v69
	v_cndmask_b32_e64 v75, v67, v75, s[4:5]
	v_fmac_f32_dpp v68, v83, v135 row_ror:15 row_mask:0xf bank_mask:0xf bound_ctrl:1
	v_add_f32_e32 v68, v143, v68
	v_cndmask_b32_e64 v91, v101, v67, s[6:7]
	v_mul_f32_e32 v65, v68, v65
	v_add_f32_e32 v68, 1.0, v69
	v_mul_f32_dpp v69, v75, v157 row_ror:1 row_mask:0xf bank_mask:0xf bound_ctrl:1
	v_mov_b32_dpp v90, v91 row_ror:15 row_mask:0xf bank_mask:0xf bound_ctrl:1
	v_fmac_f32_e32 v69, v149, v67
	v_fmac_f32_e32 v69, v153, v90
	v_rcp_f32_e32 v68, v68
	v_add_f32_e32 v67, v161, v69
	v_mul_f32_e32 v69, 0xbfb8aa3b, v67
	v_cndmask_b32_e64 v78, v70, v78, s[4:5]
	v_exp_f32_e32 v69, v69
	v_cndmask_b32_e64 v84, v108, v70, s[6:7]
	v_mul_f32_e32 v66, v66, v68
	v_mul_f32_dpp v68, v78, v132 row_ror:1 row_mask:0xf bank_mask:0xf bound_ctrl:1
	v_fmac_f32_e32 v68, v70, v140
	v_cndmask_b32_e64 v79, v71, v79, s[4:5]
	v_add_f32_e32 v69, 1.0, v69
	v_fmac_f32_dpp v68, v84, v136 row_ror:15 row_mask:0xf bank_mask:0xf bound_ctrl:1
	v_rcp_f32_e32 v69, v69
	v_add_f32_e32 v68, v144, v68
	v_cndmask_b32_e64 v85, v109, v71, s[6:7]
	v_mul_f32_e32 v66, v68, v66
	v_mul_f32_dpp v68, v79, v133 row_ror:1 row_mask:0xf bank_mask:0xf bound_ctrl:1
	v_fmac_f32_dpp v72, v82, v134 row_ror:15 row_mask:0xf bank_mask:0xf bound_ctrl:1
	v_fmac_f32_e32 v68, v71, v141
	v_add_f32_e32 v72, v142, v72
	v_fmac_f32_dpp v68, v85, v137 row_ror:15 row_mask:0xf bank_mask:0xf bound_ctrl:1
	v_mul_f32_e32 v64, v72, v64
	v_mul_f32_e32 v67, v67, v69
	v_add_f32_e32 v68, v145, v68
	v_mul_f32_e32 v67, v68, v67
	v_cvt_pk_bf16_f32 v64, v64, v65
	v_cvt_pk_bf16_f32 v65, v66, v67
	v_mov_b32_e32 v124, 0
	v_mov_b32_e32 v136, 0
	v_mov_b32_e32 v137, 0
	v_mov_b32_e32 v138, 0
	v_mov_b32_e32 v139, 0
	v_mov_b32_e32 v140, 0
	v_mov_b32_e32 v141, 0
	v_mov_b32_e32 v142, 0
	v_mov_b32_e32 v143, 0
	s_and_saveexec_b64 s[78:79], s[76:77]
	s_cbranch_execz .LBB0_1235
	v_add_u32_e32 v78, s19, v227
	ds_read_b128 v[140:143], v78 offset:272
	ds_read_b128 v[136:139], v78 offset:304

.LBB0_1237:
	s_or_b64 exec, exec, s[76:77]
	v_readlane_b32 s8, v255, 9
	s_lshl_b32 s18, s39, 8
	s_nop 0
	v_add_u32_e32 v78, s8, v194
	s_waitcnt lgkmcnt(0)
	v_cndmask_b32_e64 v91, v56, v136, s[4:5]
	v_cndmask_b32_e64 v123, v48, v56, s[6:7]
	v_cndmask_b32_e64 v98, v57, v137, s[4:5]
	s_waitcnt vmcnt(3)
	v_mul_f32_dpp v91, v91, v212 row_ror:1 row_mask:0xf bank_mask:0xf bound_ctrl:1
	s_waitcnt vmcnt(2)
	v_fmac_f32_e32 v91, v228, v56
	s_waitcnt vmcnt(1)
	v_fmac_f32_dpp v91, v123, v232 row_ror:15 row_mask:0xf bank_mask:0xf bound_ctrl:1
	s_waitcnt vmcnt(0)
	v_add_f32_e32 v91, v236, v91
	v_mul_f32_e32 v123, 0xbfb8aa3b, v91
	v_cndmask_b32_e64 v130, v49, v57, s[6:7]
	v_exp_f32_e32 v123, v123
	v_mul_f32_dpp v98, v98, v213 row_ror:1 row_mask:0xf bank_mask:0xf bound_ctrl:1
	v_fmac_f32_e32 v98, v229, v57
	v_fmac_f32_dpp v98, v130, v233 row_ror:15 row_mask:0xf bank_mask:0xf bound_ctrl:1
	v_add_f32_e32 v98, v237, v98
	v_add_f32_e32 v123, 1.0, v123
	v_mul_f32_e32 v130, 0xbfb8aa3b, v98
	v_rcp_f32_e32 v123, v123
	v_exp_f32_e32 v130, v130
	v_cndmask_b32_e64 v79, v60, v140, s[4:5]
	v_cndmask_b32_e64 v107, v52, v60, s[6:7]
	v_mul_f32_e32 v91, v91, v123
	v_add_f32_e32 v123, 1.0, v130
	v_mul_f32_dpp v79, v79, v164 row_ror:1 row_mask:0xf bank_mask:0xf bound_ctrl:1
	v_rcp_f32_e32 v123, v123
	v_fmac_f32_e32 v79, v60, v168
	v_cndmask_b32_e64 v99, v58, v138, s[4:5]
	v_fmac_f32_dpp v79, v107, v172 row_ror:15 row_mask:0xf bank_mask:0xf bound_ctrl:1
	v_add_f32_e32 v79, v204, v79
	v_cndmask_b32_e64 v131, v50, v58, s[6:7]
	v_mul_f32_e32 v79, v79, v91
	v_mul_f32_e32 v91, v98, v123
	v_mul_f32_dpp v98, v99, v214 row_ror:1 row_mask:0xf bank_mask:0xf bound_ctrl:1
	v_fmac_f32_e32 v98, v230, v58
	v_fmac_f32_dpp v98, v131, v234 row_ror:15 row_mask:0xf bank_mask:0xf bound_ctrl:1
	v_cndmask_b32_e64 v82, v61, v141, s[4:5]
	v_add_f32_e32 v98, v238, v98
	v_mul_f32_e32 v99, 0xbfb8aa3b, v98
	v_cndmask_b32_e64 v118, v53, v61, s[6:7]
	v_mul_f32_dpp v82, v82, v165 row_ror:1 row_mask:0xf bank_mask:0xf bound_ctrl:1
	v_exp_f32_e32 v99, v99
	v_fmac_f32_e32 v82, v61, v169
	v_cndmask_b32_e64 v106, v59, v139, s[4:5]
	v_fmac_f32_dpp v82, v118, v173 row_ror:15 row_mask:0xf bank_mask:0xf bound_ctrl:1
	v_add_f32_e32 v82, v205, v82
	v_cndmask_b32_e64 v136, v51, v59, s[6:7]
	v_mul_f32_e32 v82, v82, v91
	v_add_f32_e32 v91, 1.0, v99
	v_mul_f32_dpp v99, v106, v215 row_ror:1 row_mask:0xf bank_mask:0xf bound_ctrl:1
	v_mov_b32_dpp v136, v136 row_ror:15 row_mask:0xf bank_mask:0xf bound_ctrl:1
	v_fmac_f32_e32 v99, v231, v59
	v_fmac_f32_e32 v99, v235, v136
	v_add_f32_e32 v99, v239, v99
	v_mul_f32_e32 v106, 0xbfb8aa3b, v99
	v_rcp_f32_e32 v91, v91
	v_exp_f32_e32 v106, v106
	v_cndmask_b32_e64 v83, v62, v142, s[4:5]
	v_cndmask_b32_e64 v90, v63, v143, s[4:5]
	v_mul_f32_e32 v91, v98, v91
	v_add_f32_e32 v98, 1.0, v106
	v_cndmask_b32_e64 v119, v54, v62, s[6:7]
	v_mul_f32_dpp v83, v83, v166 row_ror:1 row_mask:0xf bank_mask:0xf bound_ctrl:1
	v_rcp_f32_e32 v98, v98
	v_cndmask_b32_e64 v122, v55, v63, s[6:7]
	v_fmac_f32_e32 v83, v62, v170
	v_mul_f32_dpp v90, v90, v167 row_ror:1 row_mask:0xf bank_mask:0xf bound_ctrl:1
	v_cmp_ne_u32_e32 vcc, 0, v78
	s_movk_i32 s35, 0xff
	v_fmac_f32_dpp v83, v119, v174 row_ror:15 row_mask:0xf bank_mask:0xf bound_ctrl:1
	v_fmac_f32_e32 v90, v63, v171
	s_or_b64 s[8:9], s[66:67], vcc
	v_cmp_ne_u32_e32 vcc, s35, v78
	v_add_f32_e32 v83, v206, v83
	v_fmac_f32_dpp v90, v122, v175 row_ror:15 row_mask:0xf bank_mask:0xf bound_ctrl:1
	s_or_b64 s[76:77], s[72:73], vcc
	v_mul_f32_e32 v83, v83, v91
	v_mul_f32_e32 v91, v99, v98
	v_add_f32_e32 v90, v207, v90
	s_and_b64 s[76:77], s[8:9], s[76:77]
	v_mul_f32_e32 v90, v90, v91
	v_cvt_pk_bf16_f32 v130, v79, v82
	v_cvt_pk_bf16_f32 v131, v83, v90
	s_and_saveexec_b64 s[8:9], s[76:77]
	s_cbranch_execz .LBB0_1239
	v_add_u32_e32 v79, s18, v78
	v_mov_b64_e32 v[82:83], s[12:13]
	s_movk_i32 s35, 0x2b00
	v_mad_i64_i32 v[82:83], s[76:77], v79, s35, v[82:83]
	v_lshl_add_u64 v[82:83], v[192:193], 1, v[82:83]
	global_store_dwordx4 v[82:83], v[128:131], off
.LBB0_1239:
	s_or_b64 exec, exec, s[8:9]
	v_add_u32_e32 v79, 16, v78
	v_cndmask_b32_e64 v56, v48, v56, s[4:5]
	v_cndmask_b32_e64 v98, v40, v48, s[6:7]
	v_cndmask_b32_e64 v57, v49, v57, s[4:5]
	v_mul_f32_dpp v56, v56, v212 row_ror:1 row_mask:0xf bank_mask:0xf bound_ctrl:1
	v_fmac_f32_e32 v56, v48, v228
	v_fmac_f32_dpp v56, v98, v232 row_ror:15 row_mask:0xf bank_mask:0xf bound_ctrl:1
	v_add_f32_e32 v56, v236, v56
	v_mul_f32_e32 v98, 0xbfb8aa3b, v56
	v_cndmask_b32_e64 v99, v41, v49, s[6:7]
	v_exp_f32_e32 v98, v98
	v_mul_f32_dpp v57, v57, v213 row_ror:1 row_mask:0xf bank_mask:0xf bound_ctrl:1
	v_fmac_f32_e32 v57, v49, v229
	v_fmac_f32_dpp v57, v99, v233 row_ror:15 row_mask:0xf bank_mask:0xf bound_ctrl:1
	v_add_f32_e32 v57, v237, v57
	v_cndmask_b32_e64 v60, v52, v60, s[4:5]
	v_cndmask_b32_e64 v58, v50, v58, s[4:5]
	v_add_f32_e32 v98, 1.0, v98
	v_mul_f32_e32 v99, 0xbfb8aa3b, v57
	v_rcp_f32_e32 v98, v98
	v_exp_f32_e32 v99, v99
	v_cndmask_b32_e64 v82, v44, v52, s[6:7]
	v_cndmask_b32_e64 v106, v42, v50, s[6:7]
	v_mul_f32_dpp v60, v60, v164 row_ror:1 row_mask:0xf bank_mask:0xf bound_ctrl:1
	v_mul_f32_dpp v58, v58, v214 row_ror:1 row_mask:0xf bank_mask:0xf bound_ctrl:1
	v_fmac_f32_e32 v60, v52, v168
	v_fmac_f32_e32 v58, v50, v230
	v_cndmask_b32_e64 v61, v53, v61, s[4:5]
	v_fmac_f32_dpp v60, v82, v172 row_ror:15 row_mask:0xf bank_mask:0xf bound_ctrl:1
	v_fmac_f32_dpp v58, v106, v234 row_ror:15 row_mask:0xf bank_mask:0xf bound_ctrl:1
	v_mul_f32_e32 v56, v56, v98
	v_add_f32_e32 v98, 1.0, v99
	v_add_f32_e32 v60, v204, v60
	v_add_f32_e32 v58, v238, v58
	v_rcp_f32_e32 v98, v98
	v_mul_f32_e32 v56, v60, v56
	v_mul_f32_dpp v60, v61, v165 row_ror:1 row_mask:0xf bank_mask:0xf bound_ctrl:1
	v_mul_f32_e32 v61, 0xbfb8aa3b, v58
	v_cndmask_b32_e64 v59, v51, v59, s[4:5]
	v_cndmask_b32_e64 v83, v45, v53, s[6:7]
	v_exp_f32_e32 v61, v61
	v_fmac_f32_e32 v60, v53, v169
	v_cndmask_b32_e64 v107, v43, v51, s[6:7]
	v_fmac_f32_dpp v60, v83, v173 row_ror:15 row_mask:0xf bank_mask:0xf bound_ctrl:1
	v_mul_f32_dpp v59, v59, v215 row_ror:1 row_mask:0xf bank_mask:0xf bound_ctrl:1
	v_mul_f32_e32 v57, v57, v98
	v_add_f32_e32 v60, v205, v60
	v_fmac_f32_e32 v59, v51, v231
	v_mul_f32_e32 v57, v60, v57
	v_add_f32_e32 v60, 1.0, v61
	v_fmac_f32_dpp v59, v107, v235 row_ror:15 row_mask:0xf bank_mask:0xf bound_ctrl:1
	v_rcp_f32_e32 v60, v60
	v_add_f32_e32 v59, v239, v59
	v_mul_f32_e32 v61, 0xbfb8aa3b, v59
	v_cndmask_b32_e64 v62, v54, v62, s[4:5]
	v_exp_f32_e32 v61, v61
	v_cndmask_b32_e64 v90, v46, v54, s[6:7]
	v_mul_f32_e32 v58, v58, v60
	v_mul_f32_dpp v60, v62, v166 row_ror:1 row_mask:0xf bank_mask:0xf bound_ctrl:1
	v_fmac_f32_e32 v60, v54, v170
	v_cndmask_b32_e64 v63, v55, v63, s[4:5]
	v_add_f32_e32 v61, 1.0, v61
	v_fmac_f32_dpp v60, v90, v174 row_ror:15 row_mask:0xf bank_mask:0xf bound_ctrl:1
	v_rcp_f32_e32 v61, v61
	v_add_f32_e32 v60, v206, v60
	v_cndmask_b32_e64 v91, v47, v55, s[6:7]
	v_mul_f32_e32 v58, v60, v58
	v_mul_f32_dpp v60, v63, v167 row_ror:1 row_mask:0xf bank_mask:0xf bound_ctrl:1
	v_cmp_ne_u32_e32 vcc, 0, v79
	s_movk_i32 s35, 0xff
	v_fmac_f32_e32 v60, v55, v171
	s_or_b64 s[8:9], s[66:67], vcc
	v_cmp_ne_u32_e32 vcc, s35, v79
	v_fmac_f32_dpp v60, v91, v175 row_ror:15 row_mask:0xf bank_mask:0xf bound_ctrl:1
	s_or_b64 s[76:77], s[72:73], vcc
	v_mul_f32_e32 v59, v59, v61
	v_add_f32_e32 v60, v207, v60
	s_and_b64 s[76:77], s[8:9], s[76:77]
	v_mul_f32_e32 v59, v60, v59
	v_cvt_pk_bf16_f32 v122, v56, v57
	v_cvt_pk_bf16_f32 v123, v58, v59
	s_and_saveexec_b64 s[8:9], s[76:77]
	s_cbranch_execz .LBB0_1241
	v_add_u32_e32 v58, s18, v79
	v_mov_b64_e32 v[56:57], s[12:13]
	s_movk_i32 s35, 0x2b00
	v_mad_i64_i32 v[56:57], s[76:77], v58, s35, v[56:57]
	v_lshl_add_u64 v[56:57], v[192:193], 1, v[56:57]
	global_store_dwordx4 v[56:57], v[120:123], off
.LBB0_1241:
	s_or_b64 exec, exec, s[8:9]
	v_add_u32_e32 v56, 32, v78
	v_cndmask_b32_e64 v48, v40, v48, s[4:5]
	v_cndmask_b32_e64 v61, v32, v40, s[6:7]
	v_cndmask_b32_e64 v49, v41, v49, s[4:5]
	v_mul_f32_dpp v48, v48, v212 row_ror:1 row_mask:0xf bank_mask:0xf bound_ctrl:1
	v_fmac_f32_e32 v48, v40, v228
	v_fmac_f32_dpp v48, v61, v232 row_ror:15 row_mask:0xf bank_mask:0xf bound_ctrl:1
	v_add_f32_e32 v48, v236, v48
	v_mul_f32_e32 v61, 0xbfb8aa3b, v48
	v_cndmask_b32_e64 v62, v33, v41, s[6:7]
	v_exp_f32_e32 v61, v61
	v_mul_f32_dpp v49, v49, v213 row_ror:1 row_mask:0xf bank_mask:0xf bound_ctrl:1
	v_fmac_f32_e32 v49, v41, v229
	v_fmac_f32_dpp v49, v62, v233 row_ror:15 row_mask:0xf bank_mask:0xf bound_ctrl:1
	v_add_f32_e32 v49, v237, v49
	v_cndmask_b32_e64 v52, v44, v52, s[4:5]
	v_cndmask_b32_e64 v50, v42, v50, s[4:5]
	v_add_f32_e32 v61, 1.0, v61
	v_mul_f32_e32 v62, 0xbfb8aa3b, v49
	v_rcp_f32_e32 v61, v61
	v_exp_f32_e32 v62, v62
	v_cndmask_b32_e64 v57, v36, v44, s[6:7]
	v_cndmask_b32_e64 v63, v34, v42, s[6:7]
	v_mul_f32_dpp v52, v52, v164 row_ror:1 row_mask:0xf bank_mask:0xf bound_ctrl:1
	v_mul_f32_dpp v50, v50, v214 row_ror:1 row_mask:0xf bank_mask:0xf bound_ctrl:1
	v_mov_b32_dpp v57, v57 row_ror:15 row_mask:0xf bank_mask:0xf bound_ctrl:1
	v_mov_b32_dpp v63, v63 row_ror:15 row_mask:0xf bank_mask:0xf bound_ctrl:1
	v_fmac_f32_e32 v52, v44, v168
	v_fmac_f32_e32 v50, v42, v230
	v_cndmask_b32_e64 v53, v45, v53, s[4:5]
	v_fmac_f32_e32 v52, v172, v57
	v_fmac_f32_e32 v50, v234, v63
	v_mul_f32_e32 v48, v48, v61
	v_add_f32_e32 v61, 1.0, v62
	v_add_f32_e32 v52, v204, v52
	v_add_f32_e32 v50, v238, v50
	v_rcp_f32_e32 v61, v61
	v_mul_f32_e32 v48, v52, v48
	v_mul_f32_dpp v52, v53, v165 row_ror:1 row_mask:0xf bank_mask:0xf bound_ctrl:1
	v_mul_f32_e32 v53, 0xbfb8aa3b, v50
	v_cndmask_b32_e64 v51, v43, v51, s[4:5]
	v_cndmask_b32_e64 v58, v37, v45, s[6:7]
	v_exp_f32_e32 v53, v53
	s_nop 0
	v_mov_b32_dpp v58, v58 row_ror:15 row_mask:0xf bank_mask:0xf bound_ctrl:1
	v_fmac_f32_e32 v52, v45, v169
	v_cndmask_b32_e64 v79, v35, v43, s[6:7]
	v_fmac_f32_e32 v52, v173, v58
	v_mul_f32_dpp v51, v51, v215 row_ror:1 row_mask:0xf bank_mask:0xf bound_ctrl:1
	v_mov_b32_dpp v79, v79 row_ror:15 row_mask:0xf bank_mask:0xf bound_ctrl:1
	v_mul_f32_e32 v49, v49, v61
	v_add_f32_e32 v52, v205, v52
	v_fmac_f32_e32 v51, v43, v231
	v_mul_f32_e32 v49, v52, v49
	v_add_f32_e32 v52, 1.0, v53
	v_fmac_f32_e32 v51, v235, v79
	v_rcp_f32_e32 v52, v52
	v_add_f32_e32 v51, v239, v51
	v_mul_f32_e32 v53, 0xbfb8aa3b, v51
	v_cndmask_b32_e64 v54, v46, v54, s[4:5]
	v_exp_f32_e32 v53, v53
	v_cndmask_b32_e64 v59, v38, v46, s[6:7]
	v_mul_f32_e32 v50, v50, v52
	v_mul_f32_dpp v52, v54, v166 row_ror:1 row_mask:0xf bank_mask:0xf bound_ctrl:1
	v_mov_b32_dpp v59, v59 row_ror:15 row_mask:0xf bank_mask:0xf bound_ctrl:1
	v_fmac_f32_e32 v52, v46, v170
	v_cndmask_b32_e64 v55, v47, v55, s[4:5]
	v_add_f32_e32 v53, 1.0, v53
	v_fmac_f32_e32 v52, v174, v59
	v_rcp_f32_e32 v53, v53
	v_add_f32_e32 v52, v206, v52
	v_cndmask_b32_e64 v60, v39, v47, s[6:7]
	v_mul_f32_e32 v50, v52, v50
	v_mul_f32_dpp v52, v55, v167 row_ror:1 row_mask:0xf bank_mask:0xf bound_ctrl:1
	v_cmp_ne_u32_e32 vcc, 0, v56
	s_movk_i32 s35, 0xff
	v_mov_b32_dpp v60, v60 row_ror:15 row_mask:0xf bank_mask:0xf bound_ctrl:1
	v_fmac_f32_e32 v52, v47, v171
	s_or_b64 s[8:9], s[66:67], vcc
	v_cmp_ne_u32_e32 vcc, s35, v56
	v_fmac_f32_e32 v52, v175, v60
	s_or_b64 s[76:77], s[72:73], vcc
	v_mul_f32_e32 v51, v51, v53
	v_add_f32_e32 v52, v207, v52
	s_and_b64 s[76:77], s[8:9], s[76:77]
	v_mul_f32_e32 v51, v52, v51
	v_cvt_pk_bf16_f32 v118, v48, v49
	v_cvt_pk_bf16_f32 v119, v50, v51
	s_and_saveexec_b64 s[8:9], s[76:77]
	s_cbranch_execz .LBB0_1243
	v_add_u32_e32 v50, s18, v56
	v_mov_b64_e32 v[48:49], s[12:13]
	s_movk_i32 s35, 0x2b00
	v_mad_i64_i32 v[48:49], s[76:77], v50, s35, v[48:49]
	v_lshl_add_u64 v[48:49], v[192:193], 1, v[48:49]
	global_store_dwordx4 v[48:49], v[116:119], off
.LBB0_1243:
	s_or_b64 exec, exec, s[8:9]
	v_add_u32_e32 v48, 48, v78
	v_cndmask_b32_e64 v40, v32, v40, s[4:5]
	v_cndmask_b32_e64 v53, v124, v32, s[6:7]
	v_cndmask_b32_e64 v41, v33, v41, s[4:5]
	v_mul_f32_dpp v40, v40, v212 row_ror:1 row_mask:0xf bank_mask:0xf bound_ctrl:1
	v_mov_b32_dpp v53, v53 row_ror:15 row_mask:0xf bank_mask:0xf bound_ctrl:1
	v_fmac_f32_e32 v40, v228, v32
	v_fmac_f32_e32 v40, v232, v53
	v_add_f32_e32 v32, v236, v40
	v_mul_f32_e32 v40, 0xbfb8aa3b, v32
	v_exp_f32_e32 v40, v40
	v_cndmask_b32_e64 v54, v125, v33, s[6:7]
	v_mul_f32_dpp v41, v41, v213 row_ror:1 row_mask:0xf bank_mask:0xf bound_ctrl:1
	v_fmac_f32_e32 v41, v229, v33
	v_mov_b32_dpp v53, v54 row_ror:15 row_mask:0xf bank_mask:0xf bound_ctrl:1
	v_fmac_f32_e32 v41, v233, v53
	v_add_f32_e32 v40, 1.0, v40
	v_add_f32_e32 v33, v237, v41
	v_rcp_f32_e32 v40, v40
	v_mul_f32_e32 v41, 0xbfb8aa3b, v33
	v_exp_f32_e32 v41, v41
	v_cndmask_b32_e64 v44, v36, v44, s[4:5]
	v_mul_f32_e32 v32, v32, v40
	v_cndmask_b32_e64 v49, v132, v36, s[6:7]
	v_mul_f32_dpp v40, v44, v164 row_ror:1 row_mask:0xf bank_mask:0xf bound_ctrl:1
	v_fmac_f32_e32 v40, v36, v168
	v_add_f32_e32 v36, 1.0, v41
	v_rcp_f32_e32 v36, v36
	v_cndmask_b32_e64 v45, v37, v45, s[4:5]
	v_cndmask_b32_e64 v42, v34, v42, s[4:5]
	v_cndmask_b32_e64 v50, v133, v37, s[6:7]
	v_mul_f32_e32 v33, v33, v36
	v_mul_f32_dpp v36, v45, v165 row_ror:1 row_mask:0xf bank_mask:0xf bound_ctrl:1
	v_cndmask_b32_e64 v55, v126, v34, s[6:7]
	v_fmac_f32_e32 v36, v37, v169
	v_mul_f32_dpp v37, v42, v214 row_ror:1 row_mask:0xf bank_mask:0xf bound_ctrl:1
	v_mov_b32_dpp v54, v55 row_ror:15 row_mask:0xf bank_mask:0xf bound_ctrl:1
	v_fmac_f32_e32 v37, v230, v34
	v_fmac_f32_e32 v37, v234, v54
	v_add_f32_e32 v34, v238, v37
	v_mul_f32_e32 v37, 0xbfb8aa3b, v34
	v_exp_f32_e32 v37, v37
	v_cndmask_b32_e64 v43, v35, v43, s[4:5]
	v_fmac_f32_dpp v36, v50, v173 row_ror:15 row_mask:0xf bank_mask:0xf bound_ctrl:1
	v_add_f32_e32 v36, v205, v36
	v_cndmask_b32_e64 v56, v127, v35, s[6:7]
	v_mul_f32_e32 v33, v36, v33
	v_add_f32_e32 v36, 1.0, v37
	v_mul_f32_dpp v37, v43, v215 row_ror:1 row_mask:0xf bank_mask:0xf bound_ctrl:1
	v_mov_b32_dpp v55, v56 row_ror:15 row_mask:0xf bank_mask:0xf bound_ctrl:1
	v_fmac_f32_e32 v37, v231, v35
	v_fmac_f32_e32 v37, v235, v55
	v_rcp_f32_e32 v36, v36
	v_add_f32_e32 v35, v239, v37
	v_mul_f32_e32 v37, 0xbfb8aa3b, v35
	v_cndmask_b32_e64 v46, v38, v46, s[4:5]
	v_exp_f32_e32 v37, v37
	v_cndmask_b32_e64 v51, v134, v38, s[6:7]
	v_mul_f32_e32 v34, v34, v36
	v_mul_f32_dpp v36, v46, v166 row_ror:1 row_mask:0xf bank_mask:0xf bound_ctrl:1
	v_fmac_f32_e32 v36, v38, v170
	v_cndmask_b32_e64 v47, v39, v47, s[4:5]
	v_add_f32_e32 v37, 1.0, v37
	v_fmac_f32_dpp v36, v51, v174 row_ror:15 row_mask:0xf bank_mask:0xf bound_ctrl:1
	v_rcp_f32_e32 v37, v37
	v_add_f32_e32 v36, v206, v36
	v_cndmask_b32_e64 v52, v135, v39, s[6:7]
	v_mul_f32_e32 v34, v36, v34
	v_mul_f32_dpp v36, v47, v167 row_ror:1 row_mask:0xf bank_mask:0xf bound_ctrl:1
	v_cmp_ne_u32_e32 vcc, 0, v48
	s_movk_i32 s35, 0xff
	v_fmac_f32_e32 v36, v39, v171
	s_or_b64 s[8:9], s[66:67], vcc
	v_cmp_ne_u32_e32 vcc, s35, v48
	v_fmac_f32_dpp v40, v49, v172 row_ror:15 row_mask:0xf bank_mask:0xf bound_ctrl:1
	v_fmac_f32_dpp v36, v52, v175 row_ror:15 row_mask:0xf bank_mask:0xf bound_ctrl:1
	s_or_b64 s[76:77], s[72:73], vcc
	v_add_f32_e32 v40, v204, v40
	v_mul_f32_e32 v35, v35, v37
	v_add_f32_e32 v36, v207, v36
	s_and_b64 s[76:77], s[8:9], s[76:77]
	v_mul_f32_e32 v32, v40, v32
	v_mul_f32_e32 v35, v36, v35
	v_cvt_pk_bf16_f32 v106, v32, v33
	v_cvt_pk_bf16_f32 v107, v34, v35
	s_and_saveexec_b64 s[8:9], s[76:77]
	s_cbranch_execz .LBB0_1245
	v_add_u32_e32 v34, s18, v48
	v_mov_b64_e32 v[32:33], s[12:13]
	s_movk_i32 s35, 0x2b00
	v_mad_i64_i32 v[32:33], s[76:77], v34, s35, v[32:33]
	v_lshl_add_u64 v[32:33], v[192:193], 1, v[32:33]
	global_store_dwordx4 v[32:33], v[104:107], off

.LBB0_1249:
	s_or_b64 exec, exec, s[8:9]
	v_add_u32_e32 v48, 0x80, v78
	s_waitcnt lgkmcnt(0)
	v_cndmask_b32_e64 v40, v24, v40, s[4:5]
	v_cndmask_b32_e64 v53, v16, v24, s[6:7]
	v_cndmask_b32_e64 v41, v25, v41, s[4:5]
	v_mul_f32_dpp v40, v40, v212 row_ror:1 row_mask:0xf bank_mask:0xf bound_ctrl:1
	v_fmac_f32_e32 v40, v228, v24
	v_fmac_f32_dpp v40, v53, v232 row_ror:15 row_mask:0xf bank_mask:0xf bound_ctrl:1
	v_add_f32_e32 v40, v236, v40
	v_mul_f32_e32 v53, 0xbfb8aa3b, v40
	v_cndmask_b32_e64 v54, v17, v25, s[6:7]
	v_exp_f32_e32 v53, v53
	v_mul_f32_dpp v41, v41, v213 row_ror:1 row_mask:0xf bank_mask:0xf bound_ctrl:1
	v_fmac_f32_e32 v41, v229, v25
	v_fmac_f32_dpp v41, v54, v233 row_ror:15 row_mask:0xf bank_mask:0xf bound_ctrl:1
	v_add_f32_e32 v41, v237, v41
	v_cndmask_b32_e64 v44, v28, v44, s[4:5]
	v_cndmask_b32_e64 v42, v26, v42, s[4:5]
	v_add_f32_e32 v53, 1.0, v53
	v_mul_f32_e32 v54, 0xbfb8aa3b, v41
	v_rcp_f32_e32 v53, v53
	v_exp_f32_e32 v54, v54
	v_cndmask_b32_e64 v49, v20, v28, s[6:7]
	v_cndmask_b32_e64 v55, v18, v26, s[6:7]
	v_mul_f32_dpp v44, v44, v164 row_ror:1 row_mask:0xf bank_mask:0xf bound_ctrl:1
	v_mul_f32_dpp v42, v42, v214 row_ror:1 row_mask:0xf bank_mask:0xf bound_ctrl:1
	v_mov_b32_dpp v49, v49 row_ror:15 row_mask:0xf bank_mask:0xf bound_ctrl:1
	v_mov_b32_dpp v55, v55 row_ror:15 row_mask:0xf bank_mask:0xf bound_ctrl:1
	v_fmac_f32_e32 v44, v28, v168
	v_fmac_f32_e32 v42, v230, v26
	v_cndmask_b32_e64 v45, v29, v45, s[4:5]
	v_fmac_f32_e32 v44, v172, v49
	v_fmac_f32_e32 v42, v234, v55
	v_mul_f32_e32 v40, v40, v53
	v_add_f32_e32 v53, 1.0, v54
	v_add_f32_e32 v44, v204, v44
	v_add_f32_e32 v42, v238, v42
	v_rcp_f32_e32 v53, v53
	v_mul_f32_e32 v40, v44, v40
	v_mul_f32_dpp v44, v45, v165 row_ror:1 row_mask:0xf bank_mask:0xf bound_ctrl:1
	v_mul_f32_e32 v45, 0xbfb8aa3b, v42
	v_cndmask_b32_e64 v43, v27, v43, s[4:5]
	v_cndmask_b32_e64 v50, v21, v29, s[6:7]
	v_exp_f32_e32 v45, v45
	s_nop 0
	v_mov_b32_dpp v50, v50 row_ror:15 row_mask:0xf bank_mask:0xf bound_ctrl:1
	v_fmac_f32_e32 v44, v29, v169
	v_cndmask_b32_e64 v56, v19, v27, s[6:7]
	v_fmac_f32_e32 v44, v173, v50
	v_mul_f32_dpp v43, v43, v215 row_ror:1 row_mask:0xf bank_mask:0xf bound_ctrl:1
	v_mov_b32_dpp v56, v56 row_ror:15 row_mask:0xf bank_mask:0xf bound_ctrl:1
	v_mul_f32_e32 v41, v41, v53
	v_add_f32_e32 v44, v205, v44
	v_fmac_f32_e32 v43, v231, v27
	v_mul_f32_e32 v41, v44, v41
	v_add_f32_e32 v44, 1.0, v45
	v_fmac_f32_e32 v43, v235, v56
	v_rcp_f32_e32 v44, v44
	v_add_f32_e32 v43, v239, v43
	v_mul_f32_e32 v45, 0xbfb8aa3b, v43
	v_cndmask_b32_e64 v46, v30, v46, s[4:5]
	v_exp_f32_e32 v45, v45
	v_cndmask_b32_e64 v51, v22, v30, s[6:7]
	v_mul_f32_e32 v42, v42, v44
	v_mul_f32_dpp v44, v46, v166 row_ror:1 row_mask:0xf bank_mask:0xf bound_ctrl:1
	v_mov_b32_dpp v51, v51 row_ror:15 row_mask:0xf bank_mask:0xf bound_ctrl:1
	v_fmac_f32_e32 v44, v30, v170
	v_cndmask_b32_e64 v47, v31, v47, s[4:5]
	v_add_f32_e32 v45, 1.0, v45
	v_fmac_f32_e32 v44, v174, v51
	v_rcp_f32_e32 v45, v45
	v_add_f32_e32 v44, v206, v44
	v_cndmask_b32_e64 v52, v23, v31, s[6:7]
	v_mul_f32_e32 v42, v44, v42
	v_mul_f32_dpp v44, v47, v167 row_ror:1 row_mask:0xf bank_mask:0xf bound_ctrl:1
	v_cmp_ne_u32_e32 vcc, 0, v48
	s_movk_i32 s35, 0xff
	v_mov_b32_dpp v52, v52 row_ror:15 row_mask:0xf bank_mask:0xf bound_ctrl:1
	v_fmac_f32_e32 v44, v31, v171
	s_or_b64 s[8:9], s[66:67], vcc
	v_cmp_ne_u32_e32 vcc, s35, v48
	v_fmac_f32_e32 v44, v175, v52
	s_or_b64 s[74:75], s[72:73], vcc
	v_mul_f32_e32 v43, v43, v45
	v_add_f32_e32 v44, v207, v44
	s_and_b64 s[74:75], s[8:9], s[74:75]
	v_mul_f32_e32 v43, v44, v43
	v_cvt_pk_bf16_f32 v98, v40, v41
	v_cvt_pk_bf16_f32 v99, v42, v43
	s_and_saveexec_b64 s[8:9], s[74:75]
	s_cbranch_execz .LBB0_1251
	v_add_u32_e32 v42, s18, v48
	v_mov_b64_e32 v[40:41], s[12:13]
	s_movk_i32 s35, 0x2b00
	v_mad_i64_i32 v[40:41], s[74:75], v42, s35, v[40:41]
	v_lshl_add_u64 v[40:41], v[192:193], 1, v[40:41]
	global_store_dwordx4 v[40:41], v[96:99], off
.LBB0_1251:
	s_or_b64 exec, exec, s[8:9]
	v_add_u32_e32 v40, 0x90, v78
	v_cndmask_b32_e64 v24, v16, v24, s[4:5]
	v_cndmask_b32_e64 v45, v8, v16, s[6:7]
	v_cndmask_b32_e64 v25, v17, v25, s[4:5]
	v_mul_f32_dpp v24, v24, v212 row_ror:1 row_mask:0xf bank_mask:0xf bound_ctrl:1
	v_fmac_f32_e32 v24, v16, v228
	v_fmac_f32_dpp v24, v45, v232 row_ror:15 row_mask:0xf bank_mask:0xf bound_ctrl:1
	v_add_f32_e32 v24, v236, v24
	v_mul_f32_e32 v45, 0xbfb8aa3b, v24
	v_cndmask_b32_e64 v46, v9, v17, s[6:7]
	v_exp_f32_e32 v45, v45
	v_mul_f32_dpp v25, v25, v213 row_ror:1 row_mask:0xf bank_mask:0xf bound_ctrl:1
	v_fmac_f32_e32 v25, v17, v229
	v_fmac_f32_dpp v25, v46, v233 row_ror:15 row_mask:0xf bank_mask:0xf bound_ctrl:1
	v_add_f32_e32 v25, v237, v25
	v_cndmask_b32_e64 v28, v20, v28, s[4:5]
	v_cndmask_b32_e64 v26, v18, v26, s[4:5]
	v_add_f32_e32 v45, 1.0, v45
	v_mul_f32_e32 v46, 0xbfb8aa3b, v25
	v_rcp_f32_e32 v45, v45
	v_exp_f32_e32 v46, v46
	v_cndmask_b32_e64 v41, v12, v20, s[6:7]
	v_cndmask_b32_e64 v47, v10, v18, s[6:7]
	v_mul_f32_dpp v28, v28, v164 row_ror:1 row_mask:0xf bank_mask:0xf bound_ctrl:1
	v_mul_f32_dpp v26, v26, v214 row_ror:1 row_mask:0xf bank_mask:0xf bound_ctrl:1
	v_mov_b32_dpp v47, v47 row_ror:15 row_mask:0xf bank_mask:0xf bound_ctrl:1
	v_fmac_f32_e32 v28, v20, v168
	v_fmac_f32_e32 v26, v18, v230
	v_cndmask_b32_e64 v29, v21, v29, s[4:5]
	v_fmac_f32_dpp v28, v41, v172 row_ror:15 row_mask:0xf bank_mask:0xf bound_ctrl:1
	v_fmac_f32_e32 v26, v234, v47
	v_mul_f32_e32 v24, v24, v45
	v_add_f32_e32 v45, 1.0, v46
	v_add_f32_e32 v28, v204, v28
	v_add_f32_e32 v26, v238, v26
	v_rcp_f32_e32 v45, v45
	v_mul_f32_e32 v24, v28, v24
	v_mul_f32_dpp v28, v29, v165 row_ror:1 row_mask:0xf bank_mask:0xf bound_ctrl:1
	v_mul_f32_e32 v29, 0xbfb8aa3b, v26
	v_cndmask_b32_e64 v27, v19, v27, s[4:5]
	v_cndmask_b32_e64 v42, v13, v21, s[6:7]
	v_exp_f32_e32 v29, v29
	v_fmac_f32_e32 v28, v21, v169
	v_cndmask_b32_e64 v48, v11, v19, s[6:7]
	v_fmac_f32_dpp v28, v42, v173 row_ror:15 row_mask:0xf bank_mask:0xf bound_ctrl:1
	v_mul_f32_dpp v27, v27, v215 row_ror:1 row_mask:0xf bank_mask:0xf bound_ctrl:1
	v_mov_b32_dpp v48, v48 row_ror:15 row_mask:0xf bank_mask:0xf bound_ctrl:1
	v_mul_f32_e32 v25, v25, v45
	v_add_f32_e32 v28, v205, v28
	v_fmac_f32_e32 v27, v19, v231
	v_mul_f32_e32 v25, v28, v25
	v_add_f32_e32 v28, 1.0, v29
	v_fmac_f32_e32 v27, v235, v48
	v_rcp_f32_e32 v28, v28
	v_add_f32_e32 v27, v239, v27
	v_mul_f32_e32 v29, 0xbfb8aa3b, v27
	v_cndmask_b32_e64 v30, v22, v30, s[4:5]
	v_exp_f32_e32 v29, v29
	v_cndmask_b32_e64 v43, v14, v22, s[6:7]
	v_mul_f32_e32 v26, v26, v28
	v_mul_f32_dpp v28, v30, v166 row_ror:1 row_mask:0xf bank_mask:0xf bound_ctrl:1
	v_fmac_f32_e32 v28, v22, v170
	v_cndmask_b32_e64 v31, v23, v31, s[4:5]
	v_add_f32_e32 v29, 1.0, v29
	v_fmac_f32_dpp v28, v43, v174 row_ror:15 row_mask:0xf bank_mask:0xf bound_ctrl:1
	v_rcp_f32_e32 v29, v29
	v_add_f32_e32 v28, v206, v28
	v_cndmask_b32_e64 v44, v15, v23, s[6:7]
	v_mul_f32_e32 v26, v28, v26
	v_mul_f32_dpp v28, v31, v167 row_ror:1 row_mask:0xf bank_mask:0xf bound_ctrl:1
	v_cmp_ne_u32_e32 vcc, 0, v40
	s_movk_i32 s35, 0xff
	v_mov_b32_dpp v44, v44 row_ror:15 row_mask:0xf bank_mask:0xf bound_ctrl:1
	v_fmac_f32_e32 v28, v23, v171
	s_or_b64 s[8:9], s[66:67], vcc
	v_cmp_ne_u32_e32 vcc, s35, v40
	v_fmac_f32_e32 v28, v175, v44
	s_or_b64 s[74:75], s[72:73], vcc
	v_mul_f32_e32 v27, v27, v29
	v_add_f32_e32 v28, v207, v28
	s_and_b64 s[74:75], s[8:9], s[74:75]
	v_mul_f32_e32 v27, v28, v27
	v_cvt_pk_bf16_f32 v90, v24, v25
	v_cvt_pk_bf16_f32 v91, v26, v27
	s_and_saveexec_b64 s[8:9], s[74:75]
	s_cbranch_execz .LBB0_1253
	v_add_u32_e32 v26, s18, v40
	v_mov_b64_e32 v[24:25], s[12:13]
	s_movk_i32 s35, 0x2b00
	v_mad_i64_i32 v[24:25], s[74:75], v26, s35, v[24:25]
	v_lshl_add_u64 v[24:25], v[192:193], 1, v[24:25]
	global_store_dwordx4 v[24:25], v[88:91], off
.LBB0_1253:
	s_or_b64 exec, exec, s[8:9]
	v_add_u32_e32 v24, 0xa0, v78
	v_cndmask_b32_e64 v16, v8, v16, s[4:5]
	v_cndmask_b32_e64 v29, v0, v8, s[6:7]
	v_cndmask_b32_e64 v17, v9, v17, s[4:5]
	v_mul_f32_dpp v16, v16, v212 row_ror:1 row_mask:0xf bank_mask:0xf bound_ctrl:1
	v_fmac_f32_e32 v16, v8, v228
	v_fmac_f32_dpp v16, v29, v232 row_ror:15 row_mask:0xf bank_mask:0xf bound_ctrl:1
	v_add_f32_e32 v16, v236, v16
	v_mul_f32_e32 v29, 0xbfb8aa3b, v16
	v_cndmask_b32_e64 v30, v1, v9, s[6:7]
	v_exp_f32_e32 v29, v29
	v_mul_f32_dpp v17, v17, v213 row_ror:1 row_mask:0xf bank_mask:0xf bound_ctrl:1
	v_fmac_f32_e32 v17, v9, v229
	v_fmac_f32_dpp v17, v30, v233 row_ror:15 row_mask:0xf bank_mask:0xf bound_ctrl:1
	v_add_f32_e32 v17, v237, v17
	v_cndmask_b32_e64 v20, v12, v20, s[4:5]
	v_cndmask_b32_e64 v18, v10, v18, s[4:5]
	v_add_f32_e32 v29, 1.0, v29
	v_mul_f32_e32 v30, 0xbfb8aa3b, v17
	v_rcp_f32_e32 v29, v29
	v_exp_f32_e32 v30, v30
	v_cndmask_b32_e64 v25, v4, v12, s[6:7]
	v_cndmask_b32_e64 v31, v2, v10, s[6:7]
	v_mul_f32_dpp v20, v20, v164 row_ror:1 row_mask:0xf bank_mask:0xf bound_ctrl:1
	v_mul_f32_dpp v18, v18, v214 row_ror:1 row_mask:0xf bank_mask:0xf bound_ctrl:1
	v_fmac_f32_e32 v20, v12, v168
	v_fmac_f32_e32 v18, v10, v230
	v_cndmask_b32_e64 v21, v13, v21, s[4:5]
	v_fmac_f32_dpp v20, v25, v172 row_ror:15 row_mask:0xf bank_mask:0xf bound_ctrl:1
	v_fmac_f32_dpp v18, v31, v234 row_ror:15 row_mask:0xf bank_mask:0xf bound_ctrl:1
	v_mul_f32_e32 v16, v16, v29
	v_add_f32_e32 v29, 1.0, v30
	v_add_f32_e32 v20, v204, v20
	v_add_f32_e32 v18, v238, v18
	v_rcp_f32_e32 v29, v29
	v_mul_f32_e32 v16, v20, v16
	v_mul_f32_dpp v20, v21, v165 row_ror:1 row_mask:0xf bank_mask:0xf bound_ctrl:1
	v_mul_f32_e32 v21, 0xbfb8aa3b, v18
	v_cndmask_b32_e64 v19, v11, v19, s[4:5]
	v_cndmask_b32_e64 v26, v5, v13, s[6:7]
	v_exp_f32_e32 v21, v21
	v_fmac_f32_e32 v20, v13, v169
	v_cndmask_b32_e64 v40, v3, v11, s[6:7]
	v_fmac_f32_dpp v20, v26, v173 row_ror:15 row_mask:0xf bank_mask:0xf bound_ctrl:1
	v_mul_f32_dpp v19, v19, v215 row_ror:1 row_mask:0xf bank_mask:0xf bound_ctrl:1
	v_mul_f32_e32 v17, v17, v29
	v_add_f32_e32 v20, v205, v20
	v_fmac_f32_e32 v19, v11, v231
	v_mul_f32_e32 v17, v20, v17
	v_add_f32_e32 v20, 1.0, v21
	v_fmac_f32_dpp v19, v40, v235 row_ror:15 row_mask:0xf bank_mask:0xf bound_ctrl:1
	v_rcp_f32_e32 v20, v20
	v_add_f32_e32 v19, v239, v19
	v_mul_f32_e32 v21, 0xbfb8aa3b, v19
	v_cndmask_b32_e64 v22, v14, v22, s[4:5]
	v_exp_f32_e32 v21, v21
	v_cndmask_b32_e64 v27, v6, v14, s[6:7]
	v_mul_f32_e32 v18, v18, v20
	v_mul_f32_dpp v20, v22, v166 row_ror:1 row_mask:0xf bank_mask:0xf bound_ctrl:1
	v_fmac_f32_e32 v20, v14, v170
	v_cndmask_b32_e64 v23, v15, v23, s[4:5]
	v_add_f32_e32 v21, 1.0, v21
	v_fmac_f32_dpp v20, v27, v174 row_ror:15 row_mask:0xf bank_mask:0xf bound_ctrl:1
	v_rcp_f32_e32 v21, v21
	v_add_f32_e32 v20, v206, v20
	v_cndmask_b32_e64 v28, v7, v15, s[6:7]
	v_mul_f32_e32 v18, v20, v18
	v_mul_f32_dpp v20, v23, v167 row_ror:1 row_mask:0xf bank_mask:0xf bound_ctrl:1
	v_cmp_ne_u32_e32 vcc, 0, v24
	s_movk_i32 s35, 0xff
	v_fmac_f32_e32 v20, v15, v171
	s_or_b64 s[8:9], s[66:67], vcc
	v_cmp_ne_u32_e32 vcc, s35, v24
	v_fmac_f32_dpp v20, v28, v175 row_ror:15 row_mask:0xf bank_mask:0xf bound_ctrl:1
	s_or_b64 s[74:75], s[72:73], vcc
	v_mul_f32_e32 v19, v19, v21
	v_add_f32_e32 v20, v207, v20
	s_and_b64 s[74:75], s[8:9], s[74:75]
	v_mul_f32_e32 v19, v20, v19
	v_cvt_pk_bf16_f32 v82, v16, v17
	v_cvt_pk_bf16_f32 v83, v18, v19
	s_and_saveexec_b64 s[8:9], s[74:75]
	s_cbranch_execz .LBB0_1255
	v_add_u32_e32 v18, s18, v24
	v_mov_b64_e32 v[16:17], s[12:13]
	s_movk_i32 s35, 0x2b00
	v_mad_i64_i32 v[16:17], s[74:75], v18, s35, v[16:17]
	v_lshl_add_u64 v[16:17], v[192:193], 1, v[16:17]
	global_store_dwordx4 v[16:17], v[80:83], off
.LBB0_1255:
	s_or_b64 exec, exec, s[8:9]
	v_add_u32_e32 v16, 0xb0, v78
	v_cndmask_b32_e64 v8, v0, v8, s[4:5]
	v_cndmask_b32_e64 v21, v32, v0, s[6:7]
	v_cndmask_b32_e64 v9, v1, v9, s[4:5]
	v_mul_f32_dpp v8, v8, v212 row_ror:1 row_mask:0xf bank_mask:0xf bound_ctrl:1
	v_mov_b32_dpp v21, v21 row_ror:15 row_mask:0xf bank_mask:0xf bound_ctrl:1
	v_fmac_f32_e32 v8, v228, v0
	v_fmac_f32_e32 v8, v232, v21
	v_add_f32_e32 v0, v236, v8
	v_mul_f32_e32 v8, 0xbfb8aa3b, v0
	v_exp_f32_e32 v8, v8
	v_cndmask_b32_e64 v22, v33, v1, s[6:7]
	v_mul_f32_dpp v9, v9, v213 row_ror:1 row_mask:0xf bank_mask:0xf bound_ctrl:1
	v_fmac_f32_e32 v9, v229, v1
	v_mov_b32_dpp v21, v22 row_ror:15 row_mask:0xf bank_mask:0xf bound_ctrl:1
	v_fmac_f32_e32 v9, v233, v21
	v_add_f32_e32 v8, 1.0, v8
	v_add_f32_e32 v1, v237, v9
	v_rcp_f32_e32 v8, v8
	v_mul_f32_e32 v9, 0xbfb8aa3b, v1
	v_exp_f32_e32 v9, v9
	v_cndmask_b32_e64 v12, v4, v12, s[4:5]
	v_mul_f32_e32 v0, v0, v8
	v_cndmask_b32_e64 v17, v36, v4, s[6:7]
	v_mul_f32_dpp v8, v12, v164 row_ror:1 row_mask:0xf bank_mask:0xf bound_ctrl:1
	v_fmac_f32_e32 v8, v4, v168
	v_add_f32_e32 v4, 1.0, v9
	v_rcp_f32_e32 v4, v4
	v_cndmask_b32_e64 v13, v5, v13, s[4:5]
	v_cndmask_b32_e64 v10, v2, v10, s[4:5]
	v_cndmask_b32_e64 v18, v37, v5, s[6:7]
	v_mul_f32_e32 v1, v1, v4
	v_mul_f32_dpp v4, v13, v165 row_ror:1 row_mask:0xf bank_mask:0xf bound_ctrl:1
	v_cndmask_b32_e64 v23, v34, v2, s[6:7]
	v_fmac_f32_e32 v4, v5, v169
	v_mul_f32_dpp v5, v10, v214 row_ror:1 row_mask:0xf bank_mask:0xf bound_ctrl:1
	v_mov_b32_dpp v22, v23 row_ror:15 row_mask:0xf bank_mask:0xf bound_ctrl:1
	v_fmac_f32_e32 v5, v230, v2
	v_fmac_f32_e32 v5, v234, v22
	v_add_f32_e32 v2, v238, v5
	v_mul_f32_e32 v5, 0xbfb8aa3b, v2
	v_exp_f32_e32 v5, v5
	v_cndmask_b32_e64 v11, v3, v11, s[4:5]
	v_fmac_f32_dpp v4, v18, v173 row_ror:15 row_mask:0xf bank_mask:0xf bound_ctrl:1
	v_add_f32_e32 v4, v205, v4
	v_cndmask_b32_e64 v24, v35, v3, s[6:7]
	v_mul_f32_e32 v1, v4, v1
	v_add_f32_e32 v4, 1.0, v5
	v_mul_f32_dpp v5, v11, v215 row_ror:1 row_mask:0xf bank_mask:0xf bound_ctrl:1
	v_mov_b32_dpp v23, v24 row_ror:15 row_mask:0xf bank_mask:0xf bound_ctrl:1
	v_fmac_f32_e32 v5, v231, v3
	v_fmac_f32_e32 v5, v235, v23
	v_rcp_f32_e32 v4, v4
	v_add_f32_e32 v3, v239, v5
	v_mul_f32_e32 v5, 0xbfb8aa3b, v3
	v_cndmask_b32_e64 v14, v6, v14, s[4:5]
	v_exp_f32_e32 v5, v5
	v_cndmask_b32_e64 v19, v38, v6, s[6:7]
	v_mul_f32_e32 v2, v2, v4
	v_mul_f32_dpp v4, v14, v166 row_ror:1 row_mask:0xf bank_mask:0xf bound_ctrl:1
	v_fmac_f32_e32 v4, v6, v170
	v_cndmask_b32_e64 v15, v7, v15, s[4:5]
	v_add_f32_e32 v5, 1.0, v5
	v_fmac_f32_dpp v4, v19, v174 row_ror:15 row_mask:0xf bank_mask:0xf bound_ctrl:1
	v_rcp_f32_e32 v5, v5
	v_add_f32_e32 v4, v206, v4
	v_cndmask_b32_e64 v20, v39, v7, s[6:7]
	v_mul_f32_e32 v2, v4, v2
	v_mul_f32_dpp v4, v15, v167 row_ror:1 row_mask:0xf bank_mask:0xf bound_ctrl:1
	v_cmp_ne_u32_e32 vcc, 0, v16
	s_movk_i32 s6, 0xff
	v_fmac_f32_e32 v4, v7, v171
	s_or_b64 s[4:5], s[66:67], vcc
	v_cmp_ne_u32_e32 vcc, s6, v16
	v_fmac_f32_dpp v8, v17, v172 row_ror:15 row_mask:0xf bank_mask:0xf bound_ctrl:1
	v_fmac_f32_dpp v4, v20, v175 row_ror:15 row_mask:0xf bank_mask:0xf bound_ctrl:1
	s_or_b64 s[6:7], s[72:73], vcc
	v_add_f32_e32 v8, v204, v8
	v_mul_f32_e32 v3, v3, v5
	v_add_f32_e32 v4, v207, v4
	s_and_b64 s[6:7], s[4:5], s[6:7]
	v_mul_f32_e32 v0, v8, v0
	v_mul_f32_e32 v3, v4, v3
	v_cvt_pk_bf16_f32 v66, v0, v1
	v_cvt_pk_bf16_f32 v67, v2, v3
	s_and_saveexec_b64 s[4:5], s[6:7]
	s_cbranch_execz .LBB0_1194
	v_add_u32_e32 v2, s18, v16
	v_mov_b64_e32 v[0:1], s[12:13]
	s_movk_i32 s6, 0x2b00
	v_mad_i64_i32 v[0:1], s[6:7], v2, s6, v[0:1]
	v_lshl_add_u64 v[0:1], v[192:193], 1, v[0:1]
	global_store_dwordx4 v[0:1], v[64:67], off
	s_branch .LBB0_1194

.LBB0_1362:
	s_add_u32 s63, s16, 0x100
	v_mov_b32_e32 v0, 0
	s_addc_u32 s66, s17, 0
	s_mov_b32 s67, -2
	v_mov_b32_e32 v1, 0
	v_mov_b64_e32 v[2:3], 0
	v_mov_b64_e32 v[4:5], 0
	v_mov_b64_e32 v[6:7], 0
	v_mov_b64_e32 v[8:9], 0
	v_mov_b64_e32 v[10:11], 0
	v_mov_b64_e32 v[12:13], 0
	v_mov_b64_e32 v[14:15], 0
	v_mov_b64_e32 v[16:17], 0
	v_mov_b64_e32 v[18:19], 0
	v_mov_b64_e32 v[20:21], 0
	v_mov_b64_e32 v[22:23], 0
	v_mov_b64_e32 v[24:25], 0
	v_mov_b64_e32 v[26:27], 0
	v_mov_b64_e32 v[28:29], 0
	v_mov_b64_e32 v[30:31], 0
	v_mov_b64_e32 v[32:33], 0
	v_mov_b64_e32 v[34:35], 0
	v_mov_b64_e32 v[36:37], 0
	v_mov_b64_e32 v[38:39], 0
	v_mov_b64_e32 v[40:41], 0
	v_mov_b64_e32 v[42:43], 0
	v_mov_b64_e32 v[44:45], 0
	v_mov_b64_e32 v[46:47], 0
	v_mov_b64_e32 v[52:53], 0
	v_mov_b64_e32 v[54:55], 0
	v_mov_b64_e32 v[56:57], 0
	v_mov_b64_e32 v[58:59], 0
	v_mov_b64_e32 v[60:61], 0
	v_mov_b64_e32 v[62:63], 0
	v_mov_b64_e32 v[64:65], 0
	v_mov_b64_e32 v[66:67], 0
	v_mov_b64_e32 v[80:81], 0
	v_mov_b64_e32 v[82:83], 0
	v_mov_b64_e32 v[84:85], 0
	v_mov_b64_e32 v[86:87], 0
	v_mov_b64_e32 v[88:89], 0
	v_mov_b64_e32 v[90:91], 0
	v_mov_b64_e32 v[92:93], 0
	v_mov_b64_e32 v[94:95], 0
	v_mov_b64_e32 v[96:97], 0
	v_mov_b64_e32 v[98:99], 0
	v_mov_b64_e32 v[100:101], 0
	v_mov_b64_e32 v[102:103], 0
	v_mov_b64_e32 v[104:105], 0
	v_mov_b64_e32 v[106:107], 0
	v_mov_b64_e32 v[108:109], 0
	v_mov_b64_e32 v[110:111], 0
	v_mov_b64_e32 v[112:113], 0
	v_mov_b64_e32 v[114:115], 0
	v_mov_b64_e32 v[116:117], 0
	v_mov_b64_e32 v[118:119], 0
	v_mov_b64_e32 v[120:121], 0
	v_mov_b64_e32 v[122:123], 0
	v_mov_b64_e32 v[124:125], 0
	v_mov_b64_e32 v[126:127], 0
	v_mov_b64_e32 v[128:129], 0
	v_mov_b64_e32 v[130:131], 0
	v_mov_b64_e32 v[132:133], 0
	v_mov_b64_e32 v[134:135], 0
	v_mov_b64_e32 v[136:137], 0
	v_mov_b64_e32 v[138:139], 0
	v_mov_b64_e32 v[140:141], 0
	v_mov_b64_e32 v[142:143], 0
